# A8: RWKV prompt scan applies decay once per 4 tokens (helper pre-scales k,e by group decay product and m,b by its inverse); same f32 math
# speedup vs baseline: 1.0246x; 1.0122x over previous
.LBB0_185:
	s_and_b32 s17, s16, 1
	s_and_saveexec_b64 s[0:1], s[36:37]
	s_xor_b64 s[8:9], exec, s[0:1]
	s_cbranch_execz .LBB0_203
	s_ashr_i32 s2, s16, 5
	v_readlane_b32 s0, v251, 28
	s_ashr_i32 s3, s2, 31
	s_bfe_u32 s12, s16, 0x40001
	v_readlane_b32 s1, v251, 29
	s_lshl_b64 s[10:11], s[2:3], 11
	s_mov_b32 s15, s1
	s_lshl_b32 s14, s12, 7
	s_lshl_b32 s18, s12, 6
	v_lshl_add_u64 v[16:17], s[10:11], 0, v[104:105]
	v_lshl_add_u64 v[34:35], v[106:107], 0, s[14:15]
	s_movk_i32 s13, 0x1800
	v_lshl_add_u64 v[36:37], v[108:109], 0, s[14:15]
	v_or_b32_e32 v2, s18, v1
	v_readlane_b32 s40, v251, 9
	v_mad_u64_u32 v[14:15], s[0:1], v16, s13, v[34:35]
	v_mad_u64_u32 v[18:19], s[0:1], v16, s13, v[36:37]
	v_lshlrev_b32_e32 v12, 2, v2
	v_readlane_b32 s44, v251, 13
	v_readlane_b32 s45, v251, 14
	v_mad_i32_i24 v15, v17, s13, v15
	v_mad_i32_i24 v19, v17, s13, v19
	v_readlane_b32 s42, v251, 11
	v_readlane_b32 s43, v251, 12
	v_add_co_u32_e32 v10, vcc, s73, v14
	global_load_dwordx4 v[2:5], v12, s[44:45]
	global_load_dwordx2 v[20:21], v[14:15], off
	global_load_dwordx2 v[22:23], v[14:15], off offset:2048
	global_load_dwordx2 v[30:31], v[18:19], off
	global_load_dwordx4 v[6:9], v12, s[42:43]
	global_load_dwordx2 v[32:33], v[18:19], off offset:2048
	v_addc_co_u32_e32 v11, vcc, 0, v15, vcc
	v_readlane_b32 s46, v251, 15
	v_readlane_b32 s47, v251, 16
	global_load_dwordx2 v[24:25], v[10:11], off
	s_nop 3
	global_load_dwordx4 v[10:13], v12, s[46:47]
	s_waitcnt vmcnt(9)
	v_or_b32_e32 v26, s17, v1
	v_cmp_eq_u32_e64 s[0:1], 0, v26
	s_lshl_b32 s19, s12, 2
	v_readlane_b32 s12, v248, 15
	v_readlane_b32 s13, v248, 16
	s_add_u32 s12, s12, s19
	s_addc_u32 s13, s13, 0
	v_lshlrev_b64 v[16:17], 6, v[16:17]
	s_mov_b64 s[24:25], s[14:15]
	v_readlane_b32 s41, v251, 10
	v_readlane_b32 s48, v251, 17
	v_readlane_b32 s49, v251, 18
	v_readlane_b32 s50, v251, 19
	v_readlane_b32 s51, v251, 20
	v_readlane_b32 s52, v251, 21
	v_readlane_b32 s53, v251, 22
	v_readlane_b32 s54, v251, 23
	v_readlane_b32 s55, v251, 24
	s_waitcnt vmcnt(7)
	v_pk_add_f32 v[38:39], v[2:3], 1.0 op_sel_hi:[1,0] neg_lo:[1,0] neg_hi:[1,0]
	s_waitcnt vmcnt(5)
	v_lshlrev_b32_e32 v28, 16, v22
	v_and_b32_e32 v29, 0xffff0000, v22
	s_waitcnt vmcnt(2)
	v_lshlrev_b32_e32 v50, 16, v32
	v_and_b32_e32 v51, 0xffff0000, v32
	v_lshlrev_b32_e32 v26, 16, v20
	v_and_b32_e32 v27, 0xffff0000, v20
	v_lshlrev_b32_e32 v54, 16, v21
	v_and_b32_e32 v55, 0xffff0000, v21
	v_lshlrev_b32_e32 v43, 16, v30
	v_and_b32_e32 v45, 0xffff0000, v30
	v_pk_mul_f32 v[20:21], v[6:7], v[28:29]
	s_waitcnt vmcnt(1)
	v_and_b32_e32 v32, 0xffff0000, v25
	v_lshlrev_b32_e32 v30, 16, v25
	v_and_b32_e32 v44, 0xffff0000, v24
	v_lshlrev_b32_e32 v42, 16, v24
	v_pk_fma_f32 v[24:25], v[50:51], v[2:3], v[38:39]
	v_pk_add_f32 v[40:41], v[4:5], 1.0 op_sel_hi:[1,0] neg_lo:[1,0] neg_hi:[1,0]
	v_lshlrev_b32_e32 v56, 16, v33
	v_and_b32_e32 v57, 0xffff0000, v33
	v_pk_mul_f32 v[60:61], v[20:21], v[50:51]
	v_pk_mul_f32 v[50:51], v[24:25], v[28:29]
	v_lshlrev_b32_e32 v52, 16, v23
	v_and_b32_e32 v53, 0xffff0000, v23
	v_lshlrev_b32_e32 v48, 16, v31
	v_and_b32_e32 v31, 0xffff0000, v31
	v_pk_fma_f32 v[58:59], v[56:57], v[4:5], v[40:41]
	v_pk_mul_f32 v[24:25], v[50:51], v[26:27]
	v_pk_mul_f32 v[22:23], v[8:9], v[52:53]
	v_fma_f32 v33, v20, v20, 0
	v_exp_f32_e32 v49, v31
	v_pk_mul_f32 v[52:53], v[58:59], v[52:53]
	v_fma_f32 v31, v60, v26, 0
	v_fma_f32 v64, v50, v26, 0
	s_waitcnt vmcnt(0)
	v_fma_f32 v24, v24, v10, 0
	v_pk_mul_f32 v[56:57], v[22:23], v[56:57]
	v_fmac_f32_e32 v33, v21, v21
	v_pk_mul_f32 v[28:29], v[52:53], v[54:55]
	v_fmac_f32_e32 v31, v61, v27
	v_fmac_f32_e32 v64, v51, v27
	v_fmac_f32_e32 v24, v25, v11
	v_exp_f32_e32 v48, v48
	v_fmac_f32_e32 v33, v22, v22
	v_fmac_f32_e32 v31, v56, v54
	v_fmac_f32_e32 v64, v52, v54
	v_fmac_f32_e32 v24, v28, v12
	v_fmac_f32_e32 v33, v23, v23
	v_fmac_f32_e32 v31, v57, v55
	v_fmac_f32_e32 v64, v53, v55
	v_fmac_f32_e32 v24, v29, v13
	s_nop 1
	v_add_f32_dpp v33, v33, v33 quad_perm:[1,0,3,2] row_mask:0xf bank_mask:0xf
	v_add_f32_dpp v24, v24, v24 quad_perm:[1,0,3,2] row_mask:0xf bank_mask:0xf
	v_add_f32_dpp v31, v31, v31 quad_perm:[1,0,3,2] row_mask:0xf bank_mask:0xf
	v_add_f32_dpp v64, v64, v64 quad_perm:[1,0,3,2] row_mask:0xf bank_mask:0xf
	v_add_f32_dpp v33, v33, v33 quad_perm:[2,3,0,1] row_mask:0xf bank_mask:0xf
	v_add_f32_dpp v24, v24, v24 quad_perm:[2,3,0,1] row_mask:0xf bank_mask:0xf
	v_add_f32_dpp v31, v31, v31 quad_perm:[2,3,0,1] row_mask:0xf bank_mask:0xf
	v_add_f32_dpp v64, v64, v64 quad_perm:[2,3,0,1] row_mask:0xf bank_mask:0xf
	v_add_f32_dpp v33, v33, v33 row_half_mirror row_mask:0xf bank_mask:0xf
	v_add_f32_dpp v24, v24, v24 row_half_mirror row_mask:0xf bank_mask:0xf
	v_add_f32_dpp v31, v31, v31 row_half_mirror row_mask:0xf bank_mask:0xf
	v_add_f32_dpp v64, v64, v64 row_half_mirror row_mask:0xf bank_mask:0xf
	v_add_f32_dpp v33, v33, v33 row_mirror row_mask:0xf bank_mask:0xf
	v_add_f32_dpp v24, v24, v24 row_mirror row_mask:0xf bank_mask:0xf
	v_add_f32_dpp v31, v31, v31 row_mirror row_mask:0xf bank_mask:0xf
	v_add_f32_dpp v64, v64, v64 row_mirror row_mask:0xf bank_mask:0xf
	s_nop 0
	v_exp_f32_e32 v46, v43
	v_max_f32_e32 v25, v33, v33
	v_max_f32_e32 v25, 0x179abe15, v25
	v_exp_f32_e32 v47, v45
	v_pk_mul_f32 v[62:63], v[48:49], v[54:55]
	v_rsq_f32_e32 v54, v25
	ds_write_b128 v126, v[46:49] offset:24576
	ds_read_b128 v[140:143], v126 offset:24320
	ds_read_b128 v[144:147], v126 offset:24064
	ds_read_b128 v[148:151], v126 offset:23808
	v_mov_b32_e32 v180, 1.0
	s_mov_b32 vcc_lo, 0xffff0000
	s_mov_b32 vcc_hi, -1
	s_waitcnt lgkmcnt(0)
	v_cndmask_b32_e32 v140, 1.0, v140, vcc
	v_cndmask_b32_e32 v141, 1.0, v141, vcc
	v_cndmask_b32_e32 v142, 1.0, v142, vcc
	v_cndmask_b32_e32 v143, 1.0, v143, vcc
	s_mov_b32 vcc_lo, 0
	s_nop 1
	v_cndmask_b32_e32 v144, 1.0, v144, vcc
	v_cndmask_b32_e32 v145, 1.0, v145, vcc
	v_cndmask_b32_e32 v146, 1.0, v146, vcc
	v_cndmask_b32_e32 v147, 1.0, v147, vcc
	s_mov_b32 vcc_hi, 0xffff0000
	s_nop 1
	v_cndmask_b32_e32 v148, 1.0, v148, vcc
	v_cndmask_b32_e32 v149, 1.0, v149, vcc
	v_cndmask_b32_e32 v150, 1.0, v150, vcc
	v_cndmask_b32_e32 v151, 1.0, v151, vcc
	v_pk_mul_f32 v[152:153], v[140:141], v[144:145]
	v_pk_mul_f32 v[154:155], v[142:143], v[146:147]
	v_pk_mul_f32 v[152:153], v[152:153], v[148:149]
	v_pk_mul_f32 v[154:155], v[154:155], v[150:151]
	v_pk_mul_f32 v[156:157], v[152:153], v[46:47]
	v_pk_mul_f32 v[158:159], v[154:155], v[48:49]
	v_rcp_f32_e32 v160, v156
	v_rcp_f32_e32 v161, v157
	v_rcp_f32_e32 v162, v158
	v_rcp_f32_e32 v163, v159
	s_nop 1
	v_cndmask_b32_e32 v160, v160, v180, vcc
	v_cndmask_b32_e32 v161, v161, v180, vcc
	v_cndmask_b32_e32 v162, v162, v180, vcc
	v_cndmask_b32_e32 v163, v163, v180, vcc
	ds_write_b128 v126, v[156:159] offset:24576
	v_pk_mul_f32 v[164:165], v[50:51], v[160:161]
	v_pk_mul_f32 v[166:167], v[52:53], v[162:163]
	ds_write_b128 v126, v[164:167] offset:16384
	v_pk_mul_f32 v[58:59], v[46:47], v[26:27]
	v_mul_f32_e32 v43, v64, v42
	v_pk_mul_f32 v[20:21], v[20:21], v[54:55] op_sel_hi:[1,0]
	v_pk_mul_f32 v[22:23], v[22:23], v[54:55] op_sel_hi:[1,0]
	v_mul_f32_e64 v46, v31, -v54
	v_pk_mul_f32 v[28:29], v[56:57], v[54:55] op_sel_hi:[1,0]
	v_pk_mul_f32 v[26:27], v[60:61], v[54:55] op_sel_hi:[1,0]
	v_pk_fma_f32 v[48:49], v[46:47], v[22:23], v[62:63] op_sel_hi:[0,1,1]
	v_pk_fma_f32 v[46:47], v[46:47], v[20:21], v[58:59] op_sel_hi:[0,1,1]
	v_pk_mul_f32 v[168:169], v[26:27], v[160:161]
	v_pk_mul_f32 v[170:171], v[28:29], v[162:163]
	ds_write_b128 v126, v[168:171] offset:32768
	v_mul_f32_e32 v172, v20, v152
	v_mul_f32_e32 v173, v21, v153
	v_mul_f32_e32 v174, v22, v154
	v_mul_f32_e32 v175, v23, v155
	v_mul_f32_e32 v176, v46, v152
	v_mul_f32_e32 v177, v47, v153
	v_mul_f32_e32 v178, v48, v154
	v_mul_f32_e32 v179, v49, v155
	v_add_u32_e32 v201, 0x2000, v126
	ds_write2_b32 v126, v172, v176 offset1:1
	ds_write2_b32 v126, v173, v177 offset0:2 offset1:3
	ds_write2_b32 v201, v174, v178 offset1:1
	ds_write2_b32 v201, v175, v179 offset0:2 offset1:3
	v_mul_f32_e32 v45, v64, v44
	v_add_u32_e32 v20, v124, v127
	v_mul_f32_e32 v31, v64, v30
	v_mul_f32_e32 v33, v64, v32
	v_lshl_add_u64 v[22:23], s[12:13], 0, v[16:17]
	ds_write_b128 v20, v[42:45] offset:40960
	ds_write_b128 v20, v[30:33] offset:40976
	s_and_saveexec_b64 s[14:15], s[0:1]
	s_cbranch_execz .LBB0_188
	global_store_dword v[22:23], v24, off
.LBB0_188:
	s_or_b64 exec, exec, s[14:15]
	v_add_co_u32_e32 v24, vcc, 0x18000, v14
	s_mov_b64 s[14:15], 0x18000
	s_nop 0
	v_addc_co_u32_e32 v25, vcc, 0, v15, vcc
	v_lshl_add_u64 v[16:17], v[14:15], 0, s[14:15]
	v_add_co_u32_e32 v14, vcc, 0x19000, v14
	global_load_dwordx2 v[24:25], v[24:25], off
	s_nop 0
	global_load_dwordx2 v[32:33], v[16:17], off offset:2048
	v_addc_co_u32_e32 v15, vcc, 0, v15, vcc
	global_load_dwordx2 v[54:55], v[14:15], off
	v_add_co_u32_e32 v14, vcc, 0x18000, v18
	v_lshl_add_u64 v[20:21], v[18:19], 0, s[14:15]
	s_nop 0
	v_addc_co_u32_e32 v15, vcc, 0, v19, vcc
	global_load_dwordx2 v[14:15], v[14:15], off
	s_nop 0
	global_load_dwordx2 v[18:19], v[20:21], off offset:2048
	s_waitcnt vmcnt(4)
	v_lshlrev_b32_e32 v50, 16, v25
	s_waitcnt vmcnt(3)
	v_and_b32_e32 v17, 0xffff0000, v32
	v_and_b32_e32 v51, 0xffff0000, v25
	s_waitcnt vmcnt(1)
	v_lshlrev_b32_e32 v16, 16, v14
	s_waitcnt vmcnt(0)
	v_lshlrev_b32_e32 v42, 16, v18
	v_and_b32_e32 v43, 0xffff0000, v18
	v_and_b32_e32 v14, 0xffff0000, v14
	v_exp_f32_e32 v26, v16
	v_lshlrev_b32_e32 v16, 16, v32
	v_pk_fma_f32 v[28:29], v[42:43], v[2:3], v[38:39]
	v_lshlrev_b32_e32 v44, 16, v15
	v_and_b32_e32 v45, 0xffff0000, v15
	v_exp_f32_e32 v27, v14
	v_lshlrev_b32_e32 v14, 16, v24
	v_and_b32_e32 v15, 0xffff0000, v24
	v_pk_mul_f32 v[30:31], v[28:29], v[16:17]
	v_lshlrev_b32_e32 v18, 16, v19
	v_pk_mul_f32 v[28:29], v[30:31], v[14:15]
	v_and_b32_e32 v19, 0xffff0000, v19
	v_fma_f32 v24, v28, v10, 0
	v_lshlrev_b32_e32 v32, 16, v33
	v_and_b32_e32 v33, 0xffff0000, v33
	v_pk_fma_f32 v[46:47], v[18:19], v[4:5], v[40:41]
	v_fmac_f32_e32 v24, v29, v11
	v_exp_f32_e32 v28, v44
	v_exp_f32_e32 v29, v45
	v_pk_mul_f32 v[44:45], v[8:9], v[32:33]
	v_pk_mul_f32 v[32:33], v[46:47], v[32:33]
	v_pk_mul_f32 v[20:21], v[6:7], v[16:17]
	v_pk_mul_f32 v[46:47], v[32:33], v[50:51]
	v_fma_f32 v48, v20, v20, 0
	v_fmac_f32_e32 v24, v46, v12
	v_fmac_f32_e32 v24, v47, v13
	v_pk_mul_f32 v[46:47], v[20:21], v[42:43]
	v_fma_f32 v17, v30, v14, 0
	v_fma_f32 v25, v46, v14, 0
	v_fmac_f32_e32 v48, v21, v21
	v_fmac_f32_e32 v17, v31, v15
	v_fmac_f32_e32 v25, v47, v15
	v_pk_mul_f32 v[18:19], v[44:45], v[18:19]
	v_fmac_f32_e32 v48, v44, v44
	v_fmac_f32_e32 v17, v32, v50
	v_fmac_f32_e32 v25, v18, v50
	v_fmac_f32_e32 v48, v45, v45
	v_fmac_f32_e32 v17, v33, v51
	v_fmac_f32_e32 v25, v19, v51
	s_nop 1
	v_add_f32_dpp v48, v48, v48 quad_perm:[1,0,3,2] row_mask:0xf bank_mask:0xf
	v_add_f32_dpp v24, v24, v24 quad_perm:[1,0,3,2] row_mask:0xf bank_mask:0xf
	v_add_f32_dpp v25, v25, v25 quad_perm:[1,0,3,2] row_mask:0xf bank_mask:0xf
	v_add_f32_dpp v17, v17, v17 quad_perm:[1,0,3,2] row_mask:0xf bank_mask:0xf
	v_add_f32_dpp v48, v48, v48 quad_perm:[2,3,0,1] row_mask:0xf bank_mask:0xf
	v_add_f32_dpp v24, v24, v24 quad_perm:[2,3,0,1] row_mask:0xf bank_mask:0xf
	v_add_f32_dpp v25, v25, v25 quad_perm:[2,3,0,1] row_mask:0xf bank_mask:0xf
	v_add_f32_dpp v17, v17, v17 quad_perm:[2,3,0,1] row_mask:0xf bank_mask:0xf
	v_add_f32_dpp v48, v48, v48 row_half_mirror row_mask:0xf bank_mask:0xf
	v_add_f32_dpp v24, v24, v24 row_half_mirror row_mask:0xf bank_mask:0xf
	v_add_f32_dpp v25, v25, v25 row_half_mirror row_mask:0xf bank_mask:0xf
	v_add_f32_dpp v17, v17, v17 row_half_mirror row_mask:0xf bank_mask:0xf
	v_add_f32_dpp v48, v48, v48 row_mirror row_mask:0xf bank_mask:0xf
	v_add_f32_dpp v24, v24, v24 row_mirror row_mask:0xf bank_mask:0xf
	v_add_f32_dpp v25, v25, v25 row_mirror row_mask:0xf bank_mask:0xf
	v_add_f32_dpp v17, v17, v17 row_mirror row_mask:0xf bank_mask:0xf
	s_nop 0
	v_pk_mul_f32 v[14:15], v[26:27], v[14:15]
	v_max_f32_e32 v16, v48, v48
	v_max_f32_e32 v16, 0x179abe15, v16
	v_rsq_f32_e32 v16, v16
	s_nop 0
	v_pk_mul_f32 v[42:43], v[20:21], v[16:17] op_sel_hi:[1,0]
	v_pk_mul_f32 v[44:45], v[44:45], v[16:17] op_sel_hi:[1,0]
	v_pk_mul_f32 v[48:49], v[18:19], v[16:17] op_sel_hi:[1,0]
	v_pk_mul_f32 v[46:47], v[46:47], v[16:17] op_sel_hi:[1,0]
	v_pk_mul_f32 v[18:19], v[28:29], v[50:51]
	v_mul_f32_e64 v16, v25, -v16
	v_pk_fma_f32 v[52:53], v[16:17], v[44:45], v[18:19] op_sel_hi:[0,1,1]
	v_pk_fma_f32 v[50:51], v[16:17], v[42:43], v[14:15] op_sel_hi:[0,1,1]
	v_and_b32_e32 v16, 0xffff0000, v55
	v_lshlrev_b32_e32 v14, 16, v55
	v_and_b32_e32 v20, 0xffff0000, v54
	v_lshlrev_b32_e32 v18, 16, v54
	v_mul_f32_e32 v19, v17, v18
	v_mul_f32_e32 v21, v17, v20
	v_add_u32_e32 v25, v124, v130
	v_mul_f32_e32 v15, v17, v14
	v_mul_f32_e32 v17, v17, v16
	ds_write_b128 v129, v[26:29] offset:24576
	ds_read_b128 v[140:143], v129 offset:24320
	ds_read_b128 v[144:147], v129 offset:24064
	ds_read_b128 v[148:151], v129 offset:23808
	v_mov_b32_e32 v180, 1.0
	s_mov_b32 vcc_lo, 0xffff0000
	s_mov_b32 vcc_hi, -1
	s_waitcnt lgkmcnt(0)
	v_cndmask_b32_e32 v140, 1.0, v140, vcc
	v_cndmask_b32_e32 v141, 1.0, v141, vcc
	v_cndmask_b32_e32 v142, 1.0, v142, vcc
	v_cndmask_b32_e32 v143, 1.0, v143, vcc
	s_mov_b32 vcc_lo, 0
	s_nop 1
	v_cndmask_b32_e32 v144, 1.0, v144, vcc
	v_cndmask_b32_e32 v145, 1.0, v145, vcc
	v_cndmask_b32_e32 v146, 1.0, v146, vcc
	v_cndmask_b32_e32 v147, 1.0, v147, vcc
	s_mov_b32 vcc_hi, 0xffff0000
	s_nop 1
	v_cndmask_b32_e32 v148, 1.0, v148, vcc
	v_cndmask_b32_e32 v149, 1.0, v149, vcc
	v_cndmask_b32_e32 v150, 1.0, v150, vcc
	v_cndmask_b32_e32 v151, 1.0, v151, vcc
	v_pk_mul_f32 v[152:153], v[140:141], v[144:145]
	v_pk_mul_f32 v[154:155], v[142:143], v[146:147]
	v_pk_mul_f32 v[152:153], v[152:153], v[148:149]
	v_pk_mul_f32 v[154:155], v[154:155], v[150:151]
	v_pk_mul_f32 v[156:157], v[152:153], v[26:27]
	v_pk_mul_f32 v[158:159], v[154:155], v[28:29]
	v_rcp_f32_e32 v160, v156
	v_rcp_f32_e32 v161, v157
	v_rcp_f32_e32 v162, v158
	v_rcp_f32_e32 v163, v159
	s_nop 1
	v_cndmask_b32_e32 v160, v160, v180, vcc
	v_cndmask_b32_e32 v161, v161, v180, vcc
	v_cndmask_b32_e32 v162, v162, v180, vcc
	v_cndmask_b32_e32 v163, v163, v180, vcc
	ds_write_b128 v129, v[156:159] offset:24576
	v_pk_mul_f32 v[164:165], v[30:31], v[160:161]
	v_pk_mul_f32 v[166:167], v[32:33], v[162:163]
	ds_write_b128 v129, v[164:167] offset:16384
	v_pk_mul_f32 v[168:169], v[46:47], v[160:161]
	v_pk_mul_f32 v[170:171], v[48:49], v[162:163]
	ds_write_b128 v129, v[168:171] offset:32768
	v_mul_f32_e32 v172, v42, v152
	v_mul_f32_e32 v173, v43, v153
	v_mul_f32_e32 v174, v44, v154
	v_mul_f32_e32 v175, v45, v155
	v_mul_f32_e32 v176, v50, v152
	v_mul_f32_e32 v177, v51, v153
	v_mul_f32_e32 v178, v52, v154
	v_mul_f32_e32 v179, v53, v155
	v_add_u32_e32 v201, 0x2000, v129
	ds_write2_b32 v129, v172, v176 offset1:1
	ds_write2_b32 v129, v173, v177 offset0:2 offset1:3
	ds_write2_b32 v201, v174, v178 offset1:1
	ds_write2_b32 v201, v175, v179 offset0:2 offset1:3
	ds_write_b128 v25, v[18:21] offset:40960
	ds_write_b128 v25, v[14:17] offset:40976
	s_and_saveexec_b64 s[14:15], s[0:1]
	s_cbranch_execz .LBB0_190
	global_store_dword v[22:23], v24, off offset:1024
.LBB0_190:
	s_or_b64 exec, exec, s[14:15]
	v_lshl_add_u64 v[42:43], v[104:105], 0, s[10:11]
	v_lshl_add_u64 v[46:47], v[42:43], 0, 32
	s_movk_i32 s20, 0x1800
	v_mad_u64_u32 v[14:15], s[14:15], v46, s20, v[34:35]
	v_mad_i32_i24 v15, v47, s20, v15
	v_add_co_u32_e32 v18, vcc, s73, v14
	v_mad_u64_u32 v[16:17], s[14:15], v46, s20, v[36:37]
	s_nop 0
	v_addc_co_u32_e32 v19, vcc, 0, v15, vcc
	v_mad_i32_i24 v17, v47, s20, v17
	global_load_dwordx2 v[20:21], v[14:15], off
	global_load_dwordx2 v[22:23], v[14:15], off offset:2048
	global_load_dwordx2 v[54:55], v[18:19], off
	s_nop 0
	global_load_dwordx2 v[18:19], v[16:17], off
	global_load_dwordx2 v[24:25], v[16:17], off offset:2048
	s_mov_b64 s[14:15], 0x18000
	v_lshl_add_u64 v[26:27], v[14:15], 0, s[14:15]
	v_lshl_add_u64 v[28:29], v[16:17], 0, s[14:15]
	s_mov_b32 s14, 0x19000
	v_add_co_u32_e32 v14, vcc, s14, v14
	s_mov_b32 s14, 0x18000
	s_nop 0
	v_addc_co_u32_e32 v15, vcc, 0, v15, vcc
	global_load_dwordx2 v[50:51], v[14:15], off offset:-4096
	global_load_dwordx2 v[48:49], v[26:27], off offset:2048
	global_load_dwordx2 v[44:45], v[14:15], off
	v_add_co_u32_e32 v14, vcc, s14, v16
	s_waitcnt vmcnt(7)
	v_lshlrev_b32_e32 v60, 16, v20
	v_addc_co_u32_e32 v15, vcc, 0, v17, vcc
	global_load_dwordx2 v[56:57], v[14:15], off
	global_load_dwordx2 v[52:53], v[28:29], off offset:2048
	s_waitcnt vmcnt(5)
	v_lshlrev_b32_e32 v28, 16, v24
	v_and_b32_e32 v29, 0xffff0000, v24
	v_lshlrev_b32_e32 v14, 16, v18
	v_and_b32_e32 v15, 0xffff0000, v18
	v_lshlrev_b32_e32 v30, 16, v19
	v_and_b32_e32 v31, 0xffff0000, v19
	v_lshlrev_b32_e32 v16, 16, v22
	v_and_b32_e32 v17, 0xffff0000, v22
	v_pk_fma_f32 v[18:19], v[28:29], v[2:3], v[38:39]
	v_and_b32_e32 v61, 0xffff0000, v20
	v_pk_mul_f32 v[18:19], v[18:19], v[16:17]
	v_pk_mul_f32 v[26:27], v[6:7], v[16:17]
	v_pk_mul_f32 v[16:17], v[18:19], v[60:61]
	v_lshlrev_b32_e32 v24, 16, v25
	v_fma_f32 v58, v16, v10, 0
	v_and_b32_e32 v25, 0xffff0000, v25
	v_fmac_f32_e32 v58, v17, v11
	v_exp_f32_e32 v16, v30
	v_exp_f32_e32 v17, v31
	v_lshlrev_b32_e32 v62, 16, v21
	v_and_b32_e32 v63, 0xffff0000, v21
	v_lshlrev_b32_e32 v20, 16, v23
	v_and_b32_e32 v21, 0xffff0000, v23
	v_pk_fma_f32 v[30:31], v[24:25], v[4:5], v[40:41]
	v_pk_mul_f32 v[64:65], v[26:27], v[28:29]
	v_fma_f32 v32, v26, v26, 0
	v_fma_f32 v59, v18, v60, 0
	v_pk_mul_f32 v[22:23], v[8:9], v[20:21]
	v_pk_mul_f32 v[20:21], v[30:31], v[20:21]
	v_fma_f32 v67, v64, v60, 0
	v_fmac_f32_e32 v32, v27, v27
	v_fmac_f32_e32 v59, v19, v61
	v_pk_mul_f32 v[30:31], v[20:21], v[62:63]
	v_fmac_f32_e32 v67, v65, v61
	v_pk_mul_f32 v[24:25], v[22:23], v[24:25]
	v_fmac_f32_e32 v32, v22, v22
	v_fmac_f32_e32 v58, v30, v12
	v_fmac_f32_e32 v59, v20, v62
	v_fmac_f32_e32 v67, v24, v62
	v_fmac_f32_e32 v32, v23, v23
	v_fmac_f32_e32 v58, v31, v13
	v_fmac_f32_e32 v59, v21, v63
	v_fmac_f32_e32 v67, v25, v63
	s_waitcnt lgkmcnt(0)
	s_barrier
	s_nop 1
	v_add_f32_dpp v32, v32, v32 quad_perm:[1,0,3,2] row_mask:0xf bank_mask:0xf
	v_add_f32_dpp v58, v58, v58 quad_perm:[1,0,3,2] row_mask:0xf bank_mask:0xf
	v_add_f32_dpp v67, v67, v67 quad_perm:[1,0,3,2] row_mask:0xf bank_mask:0xf
	v_add_f32_dpp v59, v59, v59 quad_perm:[1,0,3,2] row_mask:0xf bank_mask:0xf
	v_add_f32_dpp v32, v32, v32 quad_perm:[2,3,0,1] row_mask:0xf bank_mask:0xf
	v_add_f32_dpp v58, v58, v58 quad_perm:[2,3,0,1] row_mask:0xf bank_mask:0xf
	v_add_f32_dpp v67, v67, v67 quad_perm:[2,3,0,1] row_mask:0xf bank_mask:0xf
	v_add_f32_dpp v59, v59, v59 quad_perm:[2,3,0,1] row_mask:0xf bank_mask:0xf
	v_add_f32_dpp v32, v32, v32 row_half_mirror row_mask:0xf bank_mask:0xf
	v_add_f32_dpp v58, v58, v58 row_half_mirror row_mask:0xf bank_mask:0xf
	v_add_f32_dpp v67, v67, v67 row_half_mirror row_mask:0xf bank_mask:0xf
	v_add_f32_dpp v59, v59, v59 row_half_mirror row_mask:0xf bank_mask:0xf
	v_add_f32_dpp v32, v32, v32 row_mirror row_mask:0xf bank_mask:0xf
	v_add_f32_dpp v58, v58, v58 row_mirror row_mask:0xf bank_mask:0xf
	v_add_f32_dpp v67, v67, v67 row_mirror row_mask:0xf bank_mask:0xf
	v_add_f32_dpp v59, v59, v59 row_mirror row_mask:0xf bank_mask:0xf
	s_nop 0
	v_exp_f32_e32 v14, v14
	v_max_f32_e32 v28, v32, v32
	v_max_f32_e32 v28, 0x179abe15, v28
	v_exp_f32_e32 v15, v15
	v_rsq_f32_e32 v66, v28
	s_nop 0
	v_pk_mul_f32 v[30:31], v[26:27], v[66:67] op_sel_hi:[1,0]
	v_pk_mul_f32 v[32:33], v[22:23], v[66:67] op_sel_hi:[1,0]
	v_pk_mul_f32 v[28:29], v[24:25], v[66:67] op_sel_hi:[1,0]
	v_pk_mul_f32 v[22:23], v[14:15], v[60:61]
	v_pk_mul_f32 v[24:25], v[16:17], v[62:63]
	v_mul_f32_e64 v60, v67, -v66
	v_pk_mul_f32 v[26:27], v[64:65], v[66:67] op_sel_hi:[1,0]
	v_pk_fma_f32 v[24:25], v[60:61], v[32:33], v[24:25] op_sel_hi:[0,1,1]
	v_pk_fma_f32 v[22:23], v[60:61], v[30:31], v[22:23] op_sel_hi:[0,1,1]
	v_and_b32_e32 v62, 0xffff0000, v55
	v_lshlrev_b32_e32 v60, 16, v55
	v_and_b32_e32 v66, 0xffff0000, v54
	v_lshlrev_b32_e32 v64, 16, v54
	ds_write_b128 v133, v[14:17] offset:24576
	ds_read_b128 v[140:143], v133 offset:24320
	ds_read_b128 v[144:147], v133 offset:24064
	ds_read_b128 v[148:151], v133 offset:23808
	v_mov_b32_e32 v180, 1.0
	s_mov_b32 vcc_lo, 0xffff0000
	s_mov_b32 vcc_hi, -1
	s_waitcnt lgkmcnt(0)
	v_cndmask_b32_e32 v140, 1.0, v140, vcc
	v_cndmask_b32_e32 v141, 1.0, v141, vcc
	v_cndmask_b32_e32 v142, 1.0, v142, vcc
	v_cndmask_b32_e32 v143, 1.0, v143, vcc
	s_mov_b32 vcc_lo, 0
	s_nop 1
	v_cndmask_b32_e32 v144, 1.0, v144, vcc
	v_cndmask_b32_e32 v145, 1.0, v145, vcc
	v_cndmask_b32_e32 v146, 1.0, v146, vcc
	v_cndmask_b32_e32 v147, 1.0, v147, vcc
	s_mov_b32 vcc_hi, 0xffff0000
	s_nop 1
	v_cndmask_b32_e32 v148, 1.0, v148, vcc
	v_cndmask_b32_e32 v149, 1.0, v149, vcc
	v_cndmask_b32_e32 v150, 1.0, v150, vcc
	v_cndmask_b32_e32 v151, 1.0, v151, vcc
	v_pk_mul_f32 v[152:153], v[140:141], v[144:145]
	v_pk_mul_f32 v[154:155], v[142:143], v[146:147]
	v_pk_mul_f32 v[152:153], v[152:153], v[148:149]
	v_pk_mul_f32 v[154:155], v[154:155], v[150:151]
	v_pk_mul_f32 v[156:157], v[152:153], v[14:15]
	v_pk_mul_f32 v[158:159], v[154:155], v[16:17]
	v_rcp_f32_e32 v160, v156
	v_rcp_f32_e32 v161, v157
	v_rcp_f32_e32 v162, v158
	v_rcp_f32_e32 v163, v159
	s_nop 1
	v_cndmask_b32_e32 v160, v160, v180, vcc
	v_cndmask_b32_e32 v161, v161, v180, vcc
	v_cndmask_b32_e32 v162, v162, v180, vcc
	v_cndmask_b32_e32 v163, v163, v180, vcc
	ds_write_b128 v133, v[156:159] offset:24576
	v_pk_mul_f32 v[164:165], v[18:19], v[160:161]
	v_pk_mul_f32 v[166:167], v[20:21], v[162:163]
	ds_write_b128 v133, v[164:167] offset:16384
	v_pk_mul_f32 v[168:169], v[26:27], v[160:161]
	v_pk_mul_f32 v[170:171], v[28:29], v[162:163]
	ds_write_b128 v133, v[168:171] offset:32768
	v_mul_f32_e32 v172, v30, v152
	v_mul_f32_e32 v173, v31, v153
	v_mul_f32_e32 v174, v32, v154
	v_mul_f32_e32 v175, v33, v155
	v_mul_f32_e32 v176, v22, v152
	v_mul_f32_e32 v177, v23, v153
	v_mul_f32_e32 v178, v24, v154
	v_mul_f32_e32 v179, v25, v155
	v_add_u32_e32 v201, 0x2000, v133
	ds_write2_b32 v133, v172, v176 offset1:1
	ds_write2_b32 v133, v173, v177 offset0:2 offset1:3
	ds_write2_b32 v201, v174, v178 offset1:1
	ds_write2_b32 v201, v175, v179 offset0:2 offset1:3
	v_mul_f32_e32 v65, v59, v64
	v_mul_f32_e32 v67, v59, v66
	v_add_u32_e32 v14, v132, v127
	v_mul_f32_e32 v61, v59, v60
	v_mul_f32_e32 v63, v59, v62
	ds_write_b128 v14, v[64:67]
	ds_write_b128 v14, v[60:63] offset:16
	v_lshlrev_b64 v[14:15], 6, v[46:47]
	v_lshl_add_u64 v[14:15], s[12:13], 0, v[14:15]
	s_and_saveexec_b64 s[12:13], s[0:1]
	s_cbranch_execz .LBB0_192
	global_store_dword v[14:15], v58, off
.LBB0_192:
	s_or_b64 exec, exec, s[12:13]
	s_waitcnt vmcnt(1)
	v_lshlrev_b32_e32 v16, 16, v56
	s_waitcnt vmcnt(0)
	v_lshlrev_b32_e32 v20, 16, v52
	v_and_b32_e32 v21, 0xffff0000, v52
	v_exp_f32_e32 v18, v16
	v_lshlrev_b32_e32 v16, 16, v48
	v_and_b32_e32 v17, 0xffff0000, v48
	v_pk_fma_f32 v[22:23], v[20:21], v[2:3], v[38:39]
	v_lshlrev_b32_e32 v46, 16, v50
	v_and_b32_e32 v47, 0xffff0000, v50
	v_pk_mul_f32 v[22:23], v[22:23], v[16:17]
	v_pk_mul_f32 v[26:27], v[6:7], v[16:17]
	v_pk_mul_f32 v[16:17], v[22:23], v[46:47]
	v_lshlrev_b32_e32 v30, 16, v53
	v_and_b32_e32 v31, 0xffff0000, v53
	v_fma_f32 v16, v16, v10, 0
	v_lshlrev_b32_e32 v24, 16, v49
	v_and_b32_e32 v25, 0xffff0000, v49
	v_pk_fma_f32 v[32:33], v[30:31], v[4:5], v[40:41]
	v_pk_mul_f32 v[48:49], v[26:27], v[20:21]
	v_and_b32_e32 v19, 0xffff0000, v56
	v_fma_f32 v56, v26, v26, 0
	v_fma_f32 v58, v22, v46, 0
	v_fmac_f32_e32 v16, v17, v11
	v_lshlrev_b32_e32 v50, 16, v51
	v_and_b32_e32 v51, 0xffff0000, v51
	v_pk_mul_f32 v[28:29], v[8:9], v[24:25]
	v_pk_mul_f32 v[24:25], v[32:33], v[24:25]
	v_fma_f32 v17, v48, v46, 0
	v_fmac_f32_e32 v56, v27, v27
	v_fmac_f32_e32 v58, v23, v47
	v_pk_mul_f32 v[32:33], v[24:25], v[50:51]
	v_fmac_f32_e32 v17, v49, v47
	v_pk_mul_f32 v[30:31], v[28:29], v[30:31]
	v_fmac_f32_e32 v56, v28, v28
	v_fmac_f32_e32 v16, v32, v12
	v_fmac_f32_e32 v58, v24, v50
	v_fmac_f32_e32 v17, v30, v50
	v_fmac_f32_e32 v56, v29, v29
	v_fmac_f32_e32 v16, v33, v13
	v_fmac_f32_e32 v58, v25, v51
	v_fmac_f32_e32 v17, v31, v51
	s_nop 1
	v_add_f32_dpp v56, v56, v56 quad_perm:[1,0,3,2] row_mask:0xf bank_mask:0xf
	v_add_f32_dpp v16, v16, v16 quad_perm:[1,0,3,2] row_mask:0xf bank_mask:0xf
	v_add_f32_dpp v17, v17, v17 quad_perm:[1,0,3,2] row_mask:0xf bank_mask:0xf
	v_add_f32_dpp v58, v58, v58 quad_perm:[1,0,3,2] row_mask:0xf bank_mask:0xf
	v_add_f32_dpp v56, v56, v56 quad_perm:[2,3,0,1] row_mask:0xf bank_mask:0xf
	v_add_f32_dpp v16, v16, v16 quad_perm:[2,3,0,1] row_mask:0xf bank_mask:0xf
	v_add_f32_dpp v17, v17, v17 quad_perm:[2,3,0,1] row_mask:0xf bank_mask:0xf
	v_add_f32_dpp v58, v58, v58 quad_perm:[2,3,0,1] row_mask:0xf bank_mask:0xf
	v_add_f32_dpp v56, v56, v56 row_half_mirror row_mask:0xf bank_mask:0xf
	v_add_f32_dpp v16, v16, v16 row_half_mirror row_mask:0xf bank_mask:0xf
	v_add_f32_dpp v17, v17, v17 row_half_mirror row_mask:0xf bank_mask:0xf
	v_add_f32_dpp v58, v58, v58 row_half_mirror row_mask:0xf bank_mask:0xf
	v_add_f32_dpp v56, v56, v56 row_mirror row_mask:0xf bank_mask:0xf
	v_add_f32_dpp v16, v16, v16 row_mirror row_mask:0xf bank_mask:0xf
	v_add_f32_dpp v17, v17, v17 row_mirror row_mask:0xf bank_mask:0xf
	v_add_f32_dpp v58, v58, v58 row_mirror row_mask:0xf bank_mask:0xf
	s_nop 0
	v_lshlrev_b32_e32 v54, 16, v57
	v_max_f32_e32 v20, v56, v56
	v_and_b32_e32 v55, 0xffff0000, v57
	v_max_f32_e32 v20, 0x179abe15, v20
	v_rsq_f32_e32 v52, v20
	v_exp_f32_e32 v19, v19
	v_exp_f32_e32 v20, v54
	v_exp_f32_e32 v21, v55
	v_pk_mul_f32 v[26:27], v[26:27], v[52:53] op_sel_hi:[1,0]
	v_pk_mul_f32 v[28:29], v[28:29], v[52:53] op_sel_hi:[1,0]
	v_pk_mul_f32 v[32:33], v[30:31], v[52:53] op_sel_hi:[1,0]
	v_pk_mul_f32 v[30:31], v[48:49], v[52:53] op_sel_hi:[1,0]
	v_pk_mul_f32 v[46:47], v[18:19], v[46:47]
	v_pk_mul_f32 v[48:49], v[20:21], v[50:51]
	v_mul_f32_e64 v50, v17, -v52
	v_pk_fma_f32 v[48:49], v[50:51], v[28:29], v[48:49] op_sel_hi:[0,1,1]
	v_pk_fma_f32 v[46:47], v[50:51], v[26:27], v[46:47] op_sel_hi:[0,1,1]
	v_and_b32_e32 v52, 0xffff0000, v45
	v_lshlrev_b32_e32 v50, 16, v45
	v_and_b32_e32 v56, 0xffff0000, v44
	v_lshlrev_b32_e32 v54, 16, v44
	v_mul_f32_e32 v55, v58, v54
	v_mul_f32_e32 v57, v58, v56
	v_add_u32_e32 v17, v132, v130
	v_mul_f32_e32 v51, v58, v50
	v_mul_f32_e32 v53, v58, v52
	ds_write_b128 v134, v[18:21] offset:24576
	ds_read_b128 v[140:143], v134 offset:24320
	ds_read_b128 v[144:147], v134 offset:24064
	ds_read_b128 v[148:151], v134 offset:23808
	v_mov_b32_e32 v180, 1.0
	s_mov_b32 vcc_lo, 0xffff0000
	s_mov_b32 vcc_hi, -1
	s_waitcnt lgkmcnt(0)
	v_cndmask_b32_e32 v140, 1.0, v140, vcc
	v_cndmask_b32_e32 v141, 1.0, v141, vcc
	v_cndmask_b32_e32 v142, 1.0, v142, vcc
	v_cndmask_b32_e32 v143, 1.0, v143, vcc
	s_mov_b32 vcc_lo, 0
	s_nop 1
	v_cndmask_b32_e32 v144, 1.0, v144, vcc
	v_cndmask_b32_e32 v145, 1.0, v145, vcc
	v_cndmask_b32_e32 v146, 1.0, v146, vcc
	v_cndmask_b32_e32 v147, 1.0, v147, vcc
	s_mov_b32 vcc_hi, 0xffff0000
	s_nop 1
	v_cndmask_b32_e32 v148, 1.0, v148, vcc
	v_cndmask_b32_e32 v149, 1.0, v149, vcc
	v_cndmask_b32_e32 v150, 1.0, v150, vcc
	v_cndmask_b32_e32 v151, 1.0, v151, vcc
	v_pk_mul_f32 v[152:153], v[140:141], v[144:145]
	v_pk_mul_f32 v[154:155], v[142:143], v[146:147]
	v_pk_mul_f32 v[152:153], v[152:153], v[148:149]
	v_pk_mul_f32 v[154:155], v[154:155], v[150:151]
	v_pk_mul_f32 v[156:157], v[152:153], v[18:19]
	v_pk_mul_f32 v[158:159], v[154:155], v[20:21]
	v_rcp_f32_e32 v160, v156
	v_rcp_f32_e32 v161, v157
	v_rcp_f32_e32 v162, v158
	v_rcp_f32_e32 v163, v159
	s_nop 1
	v_cndmask_b32_e32 v160, v160, v180, vcc
	v_cndmask_b32_e32 v161, v161, v180, vcc
	v_cndmask_b32_e32 v162, v162, v180, vcc
	v_cndmask_b32_e32 v163, v163, v180, vcc
	ds_write_b128 v134, v[156:159] offset:24576
	v_pk_mul_f32 v[164:165], v[22:23], v[160:161]
	v_pk_mul_f32 v[166:167], v[24:25], v[162:163]
	ds_write_b128 v134, v[164:167] offset:16384
	v_pk_mul_f32 v[168:169], v[30:31], v[160:161]
	v_pk_mul_f32 v[170:171], v[32:33], v[162:163]
	ds_write_b128 v134, v[168:171] offset:32768
	v_mul_f32_e32 v172, v26, v152
	v_mul_f32_e32 v173, v27, v153
	v_mul_f32_e32 v174, v28, v154
	v_mul_f32_e32 v175, v29, v155
	v_mul_f32_e32 v176, v46, v152
	v_mul_f32_e32 v177, v47, v153
	v_mul_f32_e32 v178, v48, v154
	v_mul_f32_e32 v179, v49, v155
	v_add_u32_e32 v201, 0x2000, v134
	ds_write2_b32 v134, v172, v176 offset1:1
	ds_write2_b32 v134, v173, v177 offset0:2 offset1:3
	ds_write2_b32 v201, v174, v178 offset1:1
	ds_write2_b32 v201, v175, v179 offset0:2 offset1:3
	ds_write_b128 v17, v[54:57]
	ds_write_b128 v17, v[50:53] offset:16
	s_and_saveexec_b64 s[12:13], s[0:1]
	s_cbranch_execz .LBB0_194
	global_store_dword v[14:15], v16, off offset:1024

.LBB0_197:
	s_andn2_b32 s2, 0x400, s13
	v_lshl_add_u32 v48, s2, 2, v131
	v_readlane_b32 s20, v248, 7
	ds_read_b128 v[48:51], v48
	v_readlane_b32 s21, v248, 8
	s_waitcnt lgkmcnt(0)
	v_cvt_pk_bf16_f32 v48, v48, v49
	v_cvt_pk_bf16_f32 v49, v50, v51
	s_cmp_eq_u32 s12, 64
	v_readlane_b32 s22, v248, 9
	v_lshl_add_u64 v[50:51], s[20:21], 0, v[18:19]
	v_readlane_b32 s23, v248, 10
	global_store_dwordx2 v[50:51], v[48:49], off
	s_cbranch_scc1 .LBB0_196
	s_waitcnt vmcnt(7)
	v_lshlrev_b32_e32 v60, 16, v44
	v_and_b32_e32 v61, 0xffff0000, v44
	v_lshlrev_b32_e32 v52, 16, v32
	v_and_b32_e32 v53, 0xffff0000, v32
	v_pk_fma_f32 v[54:55], v[60:61], v[2:3], v[38:39]
	v_lshlrev_b32_e32 v50, 16, v46
	v_and_b32_e32 v51, 0xffff0000, v46
	v_lshlrev_b32_e32 v69, 16, v47
	v_and_b32_e32 v70, 0xffff0000, v47
	v_lshlrev_b32_e32 v46, 16, v42
	v_and_b32_e32 v47, 0xffff0000, v42
	v_pk_mul_f32 v[54:55], v[54:55], v[52:53]
	v_pk_mul_f32 v[58:59], v[6:7], v[52:53]
	v_pk_mul_f32 v[52:53], v[54:55], v[46:47]
	v_lshlrev_b32_e32 v44, 16, v45
	v_fma_f32 v32, v52, v10, 0
	v_and_b32_e32 v45, 0xffff0000, v45
	v_fmac_f32_e32 v32, v53, v11
	v_lshlrev_b32_e32 v62, 16, v43
	v_and_b32_e32 v63, 0xffff0000, v43
	v_lshlrev_b32_e32 v42, 16, v33
	v_and_b32_e32 v43, 0xffff0000, v33
	v_pk_fma_f32 v[52:53], v[44:45], v[4:5], v[40:41]
	v_pk_mul_f32 v[66:67], v[58:59], v[60:61]
	v_fma_f32 v68, v58, v58, 0
	v_fma_f32 v74, v54, v46, 0
	v_pk_mul_f32 v[64:65], v[8:9], v[42:43]
	v_pk_mul_f32 v[56:57], v[52:53], v[42:43]
	v_fma_f32 v33, v66, v46, 0
	v_fmac_f32_e32 v68, v59, v59
	v_fmac_f32_e32 v74, v55, v47
	v_pk_mul_f32 v[42:43], v[56:57], v[62:63]
	v_fmac_f32_e32 v33, v67, v47
	v_pk_mul_f32 v[60:61], v[64:65], v[44:45]
	v_fmac_f32_e32 v68, v64, v64
	v_fmac_f32_e32 v32, v42, v12
	v_fmac_f32_e32 v74, v56, v62
	v_fmac_f32_e32 v33, v60, v62
	v_fmac_f32_e32 v68, v65, v65
	v_fmac_f32_e32 v32, v43, v13
	v_fmac_f32_e32 v74, v57, v63
	v_fmac_f32_e32 v33, v61, v63
	s_nop 1
	v_add_f32_dpp v68, v68, v68 quad_perm:[1,0,3,2] row_mask:0xf bank_mask:0xf
	v_add_f32_dpp v32, v32, v32 quad_perm:[1,0,3,2] row_mask:0xf bank_mask:0xf
	v_add_f32_dpp v33, v33, v33 quad_perm:[1,0,3,2] row_mask:0xf bank_mask:0xf
	v_add_f32_dpp v74, v74, v74 quad_perm:[1,0,3,2] row_mask:0xf bank_mask:0xf
	v_add_f32_dpp v68, v68, v68 quad_perm:[2,3,0,1] row_mask:0xf bank_mask:0xf
	v_add_f32_dpp v32, v32, v32 quad_perm:[2,3,0,1] row_mask:0xf bank_mask:0xf
	v_add_f32_dpp v33, v33, v33 quad_perm:[2,3,0,1] row_mask:0xf bank_mask:0xf
	v_add_f32_dpp v74, v74, v74 quad_perm:[2,3,0,1] row_mask:0xf bank_mask:0xf
	v_add_f32_dpp v68, v68, v68 row_half_mirror row_mask:0xf bank_mask:0xf
	v_add_f32_dpp v32, v32, v32 row_half_mirror row_mask:0xf bank_mask:0xf
	v_add_f32_dpp v33, v33, v33 row_half_mirror row_mask:0xf bank_mask:0xf
	v_add_f32_dpp v74, v74, v74 row_half_mirror row_mask:0xf bank_mask:0xf
	v_add_f32_dpp v68, v68, v68 row_mirror row_mask:0xf bank_mask:0xf
	v_add_f32_dpp v32, v32, v32 row_mirror row_mask:0xf bank_mask:0xf
	v_add_f32_dpp v33, v33, v33 row_mirror row_mask:0xf bank_mask:0xf
	v_add_f32_dpp v74, v74, v74 row_mirror row_mask:0xf bank_mask:0xf
	s_nop 0
	v_exp_f32_e32 v50, v50
	v_max_f32_e32 v42, v68, v68
	v_max_f32_e32 v42, 0x179abe15, v42
	v_rsq_f32_e32 v68, v42
	v_exp_f32_e32 v51, v51
	v_exp_f32_e32 v52, v69
	v_exp_f32_e32 v53, v70
	s_bitcmp1_b32 s12, 0
	s_cselect_b32 s2, 0xe000, 0
	v_readlane_b32 s3, v251, 27
	s_add_i32 s2, s3, s2
	v_add_u32_e32 v49, s2, v122
	v_pk_mul_f32 v[42:43], v[58:59], v[68:69] op_sel_hi:[1,0]
	v_pk_mul_f32 v[44:45], v[64:65], v[68:69] op_sel_hi:[1,0]
	v_pk_mul_f32 v[58:59], v[66:67], v[68:69] op_sel_hi:[1,0]
	v_pk_mul_f32 v[46:47], v[50:51], v[46:47]
	v_pk_mul_f32 v[62:63], v[52:53], v[62:63]
	v_mul_f32_e64 v66, v33, -v68
	v_add_u32_e32 v48, s2, v123
	v_pk_mul_f32 v[60:61], v[60:61], v[68:69] op_sel_hi:[1,0]
	v_pk_fma_f32 v[64:65], v[66:67], v[44:45], v[62:63] op_sel_hi:[0,1,1]
	v_pk_fma_f32 v[62:63], v[66:67], v[42:43], v[46:47] op_sel_hi:[0,1,1]
	s_waitcnt vmcnt(4)
	v_and_b32_e32 v68, 0xffff0000, v31
	v_lshlrev_b32_e32 v66, 16, v31
	v_and_b32_e32 v72, 0xffff0000, v30
	v_lshlrev_b32_e32 v70, 16, v30
	v_add_u32_e32 v30, v49, v125
	ds_write_b128 v30, v[50:53] offset:24576
	ds_read_b128 v[140:143], v30 offset:24320
	ds_read_b128 v[144:147], v30 offset:24064
	ds_read_b128 v[148:151], v30 offset:23808
	v_mov_b32_e32 v180, 1.0
	s_mov_b32 vcc_lo, 0xffff0000
	s_mov_b32 vcc_hi, -1
	s_waitcnt lgkmcnt(0)
	v_cndmask_b32_e32 v140, 1.0, v140, vcc
	v_cndmask_b32_e32 v141, 1.0, v141, vcc
	v_cndmask_b32_e32 v142, 1.0, v142, vcc
	v_cndmask_b32_e32 v143, 1.0, v143, vcc
	s_mov_b32 vcc_lo, 0
	s_nop 1
	v_cndmask_b32_e32 v144, 1.0, v144, vcc
	v_cndmask_b32_e32 v145, 1.0, v145, vcc
	v_cndmask_b32_e32 v146, 1.0, v146, vcc
	v_cndmask_b32_e32 v147, 1.0, v147, vcc
	s_mov_b32 vcc_hi, 0xffff0000
	s_nop 1
	v_cndmask_b32_e32 v148, 1.0, v148, vcc
	v_cndmask_b32_e32 v149, 1.0, v149, vcc
	v_cndmask_b32_e32 v150, 1.0, v150, vcc
	v_cndmask_b32_e32 v151, 1.0, v151, vcc
	v_pk_mul_f32 v[152:153], v[140:141], v[144:145]
	v_pk_mul_f32 v[154:155], v[142:143], v[146:147]
	v_pk_mul_f32 v[152:153], v[152:153], v[148:149]
	v_pk_mul_f32 v[154:155], v[154:155], v[150:151]
	v_pk_mul_f32 v[156:157], v[152:153], v[50:51]
	v_pk_mul_f32 v[158:159], v[154:155], v[52:53]
	v_rcp_f32_e32 v160, v156
	v_rcp_f32_e32 v161, v157
	v_rcp_f32_e32 v162, v158
	v_rcp_f32_e32 v163, v159
	s_nop 1
	v_cndmask_b32_e32 v160, v160, v180, vcc
	v_cndmask_b32_e32 v161, v161, v180, vcc
	v_cndmask_b32_e32 v162, v162, v180, vcc
	v_cndmask_b32_e32 v163, v163, v180, vcc
	ds_write_b128 v30, v[156:159] offset:24576
	v_pk_mul_f32 v[164:165], v[54:55], v[160:161]
	v_pk_mul_f32 v[166:167], v[56:57], v[162:163]
	ds_write_b128 v30, v[164:167] offset:16384
	v_pk_mul_f32 v[168:169], v[58:59], v[160:161]
	v_pk_mul_f32 v[170:171], v[60:61], v[162:163]
	ds_write_b128 v30, v[168:171] offset:32768
	v_mul_f32_e32 v172, v42, v152
	v_mul_f32_e32 v173, v43, v153
	v_mul_f32_e32 v174, v44, v154
	v_mul_f32_e32 v175, v45, v155
	v_mul_f32_e32 v176, v62, v152
	v_mul_f32_e32 v177, v63, v153
	v_mul_f32_e32 v178, v64, v154
	v_mul_f32_e32 v179, v65, v155
	v_add_u32_e32 v201, 0x2000, v30
	ds_write2_b32 v30, v172, v176 offset1:1
	ds_write2_b32 v30, v173, v177 offset0:2 offset1:3
	ds_write2_b32 v201, v174, v178 offset1:1
	ds_write2_b32 v201, v175, v179 offset0:2 offset1:3
	v_add_u32_e32 v30, v48, v127
	v_mul_f32_e32 v71, v74, v70
	v_mul_f32_e32 v73, v74, v72
	v_mul_f32_e32 v67, v74, v66
	v_mul_f32_e32 v69, v74, v68
	ds_write_b128 v30, v[70:73] offset:40960
	ds_write_b128 v30, v[66:69] offset:40976
	v_lshl_add_u64 v[30:31], s[20:21], 0, v[16:17]
	s_and_saveexec_b64 s[2:3], s[0:1]
	s_cbranch_execz .LBB0_200
	v_add_co_u32_e32 v42, vcc, 0x15d01000, v30
	s_nop 1
	v_addc_co_u32_e32 v43, vcc, 0, v31, vcc
	global_store_dword v[42:43], v32, off
.LBB0_200:
	s_or_b64 exec, exec, s[2:3]
	s_waitcnt vmcnt(2)
	v_lshlrev_b32_e32 v32, 16, v28
	s_waitcnt vmcnt(1)
	v_lshlrev_b32_e32 v44, 16, v26
	v_and_b32_e32 v45, 0xffff0000, v26
	v_exp_f32_e32 v42, v32
	v_lshlrev_b32_e32 v32, 16, v24
	v_and_b32_e32 v33, 0xffff0000, v24
	v_pk_fma_f32 v[50:51], v[44:45], v[2:3], v[38:39]
	v_and_b32_e32 v43, 0xffff0000, v28
	v_lshlrev_b32_e32 v61, 16, v29
	v_and_b32_e32 v62, 0xffff0000, v29
	v_lshlrev_b32_e32 v28, 16, v22
	v_and_b32_e32 v29, 0xffff0000, v22
	v_pk_mul_f32 v[50:51], v[50:51], v[32:33]
	v_pk_mul_f32 v[46:47], v[6:7], v[32:33]
	v_pk_mul_f32 v[32:33], v[50:51], v[28:29]
	v_lshlrev_b32_e32 v26, 16, v27
	v_and_b32_e32 v27, 0xffff0000, v27
	v_fma_f32 v22, v32, v10, 0
	v_lshlrev_b32_e32 v24, 16, v25
	v_and_b32_e32 v25, 0xffff0000, v25
	v_pk_fma_f32 v[52:53], v[26:27], v[4:5], v[40:41]
	v_pk_mul_f32 v[58:59], v[46:47], v[44:45]
	v_fma_f32 v60, v46, v46, 0
	v_fma_f32 v65, v50, v28, 0
	v_fmac_f32_e32 v22, v33, v11
	v_lshlrev_b32_e32 v32, 16, v23
	v_and_b32_e32 v33, 0xffff0000, v23
	v_pk_mul_f32 v[54:55], v[8:9], v[24:25]
	v_pk_mul_f32 v[52:53], v[52:53], v[24:25]
	v_fma_f32 v23, v58, v28, 0
	v_fmac_f32_e32 v60, v47, v47
	v_fmac_f32_e32 v65, v51, v29
	v_pk_mul_f32 v[24:25], v[52:53], v[32:33]
	v_fmac_f32_e32 v23, v59, v29
	v_pk_mul_f32 v[56:57], v[54:55], v[26:27]
	v_fmac_f32_e32 v60, v54, v54
	v_fmac_f32_e32 v22, v24, v12
	v_fmac_f32_e32 v65, v52, v32
	v_fmac_f32_e32 v23, v56, v32
	v_fmac_f32_e32 v60, v55, v55
	v_fmac_f32_e32 v22, v25, v13
	v_fmac_f32_e32 v65, v53, v33
	v_fmac_f32_e32 v23, v57, v33
	s_nop 1
	v_add_f32_dpp v60, v60, v60 quad_perm:[1,0,3,2] row_mask:0xf bank_mask:0xf
	v_add_f32_dpp v22, v22, v22 quad_perm:[1,0,3,2] row_mask:0xf bank_mask:0xf
	v_add_f32_dpp v23, v23, v23 quad_perm:[1,0,3,2] row_mask:0xf bank_mask:0xf
	v_add_f32_dpp v65, v65, v65 quad_perm:[1,0,3,2] row_mask:0xf bank_mask:0xf
	v_add_f32_dpp v60, v60, v60 quad_perm:[2,3,0,1] row_mask:0xf bank_mask:0xf
	v_add_f32_dpp v22, v22, v22 quad_perm:[2,3,0,1] row_mask:0xf bank_mask:0xf
	v_add_f32_dpp v23, v23, v23 quad_perm:[2,3,0,1] row_mask:0xf bank_mask:0xf
	v_add_f32_dpp v65, v65, v65 quad_perm:[2,3,0,1] row_mask:0xf bank_mask:0xf
	v_add_f32_dpp v60, v60, v60 row_half_mirror row_mask:0xf bank_mask:0xf
	v_add_f32_dpp v22, v22, v22 row_half_mirror row_mask:0xf bank_mask:0xf
	v_add_f32_dpp v23, v23, v23 row_half_mirror row_mask:0xf bank_mask:0xf
	v_add_f32_dpp v65, v65, v65 row_half_mirror row_mask:0xf bank_mask:0xf
	v_add_f32_dpp v60, v60, v60 row_mirror row_mask:0xf bank_mask:0xf
	v_add_f32_dpp v22, v22, v22 row_mirror row_mask:0xf bank_mask:0xf
	v_add_f32_dpp v23, v23, v23 row_mirror row_mask:0xf bank_mask:0xf
	v_add_f32_dpp v65, v65, v65 row_mirror row_mask:0xf bank_mask:0xf
	s_nop 0
	v_exp_f32_e32 v43, v43
	v_max_f32_e32 v24, v60, v60
	v_max_f32_e32 v24, 0x179abe15, v24
	v_rsq_f32_e32 v60, v24
	v_exp_f32_e32 v44, v61
	v_exp_f32_e32 v45, v62
	v_pk_mul_f32 v[28:29], v[42:43], v[28:29]
	v_pk_mul_f32 v[24:25], v[46:47], v[60:61] op_sel_hi:[1,0]
	v_pk_mul_f32 v[26:27], v[54:55], v[60:61] op_sel_hi:[1,0]
	v_pk_mul_f32 v[32:33], v[44:45], v[32:33]
	v_mul_f32_e64 v46, v23, -v60
	v_and_b32_e32 v64, 0xffff0000, v21
	v_lshlrev_b32_e32 v62, 16, v21
	v_and_b32_e32 v68, 0xffff0000, v20
	v_lshlrev_b32_e32 v66, 16, v20
	v_add_u32_e32 v20, v49, v128
	v_pk_mul_f32 v[56:57], v[56:57], v[60:61] op_sel_hi:[1,0]
	v_pk_mul_f32 v[54:55], v[58:59], v[60:61] op_sel_hi:[1,0]
	v_pk_fma_f32 v[60:61], v[46:47], v[26:27], v[32:33] op_sel_hi:[0,1,1]
	v_pk_fma_f32 v[58:59], v[46:47], v[24:25], v[28:29] op_sel_hi:[0,1,1]
	ds_write_b128 v20, v[42:45] offset:24576
	ds_read_b128 v[140:143], v20 offset:24320
	ds_read_b128 v[144:147], v20 offset:24064
	ds_read_b128 v[148:151], v20 offset:23808
	v_mov_b32_e32 v180, 1.0
	s_mov_b32 vcc_lo, 0xffff0000
	s_mov_b32 vcc_hi, -1
	s_waitcnt lgkmcnt(0)
	v_cndmask_b32_e32 v140, 1.0, v140, vcc
	v_cndmask_b32_e32 v141, 1.0, v141, vcc
	v_cndmask_b32_e32 v142, 1.0, v142, vcc
	v_cndmask_b32_e32 v143, 1.0, v143, vcc
	s_mov_b32 vcc_lo, 0
	s_nop 1
	v_cndmask_b32_e32 v144, 1.0, v144, vcc
	v_cndmask_b32_e32 v145, 1.0, v145, vcc
	v_cndmask_b32_e32 v146, 1.0, v146, vcc
	v_cndmask_b32_e32 v147, 1.0, v147, vcc
	s_mov_b32 vcc_hi, 0xffff0000
	s_nop 1
	v_cndmask_b32_e32 v148, 1.0, v148, vcc
	v_cndmask_b32_e32 v149, 1.0, v149, vcc
	v_cndmask_b32_e32 v150, 1.0, v150, vcc
	v_cndmask_b32_e32 v151, 1.0, v151, vcc
	v_pk_mul_f32 v[152:153], v[140:141], v[144:145]
	v_pk_mul_f32 v[154:155], v[142:143], v[146:147]
	v_pk_mul_f32 v[152:153], v[152:153], v[148:149]
	v_pk_mul_f32 v[154:155], v[154:155], v[150:151]
	v_pk_mul_f32 v[156:157], v[152:153], v[42:43]
	v_pk_mul_f32 v[158:159], v[154:155], v[44:45]
	v_rcp_f32_e32 v160, v156
	v_rcp_f32_e32 v161, v157
	v_rcp_f32_e32 v162, v158
	v_rcp_f32_e32 v163, v159
	s_nop 1
	v_cndmask_b32_e32 v160, v160, v180, vcc
	v_cndmask_b32_e32 v161, v161, v180, vcc
	v_cndmask_b32_e32 v162, v162, v180, vcc
	v_cndmask_b32_e32 v163, v163, v180, vcc
	ds_write_b128 v20, v[156:159] offset:24576
	v_pk_mul_f32 v[164:165], v[50:51], v[160:161]
	v_pk_mul_f32 v[166:167], v[52:53], v[162:163]
	ds_write_b128 v20, v[164:167] offset:16384
	v_pk_mul_f32 v[168:169], v[54:55], v[160:161]
	v_pk_mul_f32 v[170:171], v[56:57], v[162:163]
	ds_write_b128 v20, v[168:171] offset:32768
	v_mul_f32_e32 v172, v24, v152
	v_mul_f32_e32 v173, v25, v153
	v_mul_f32_e32 v174, v26, v154
	v_mul_f32_e32 v175, v27, v155
	v_mul_f32_e32 v176, v58, v152
	v_mul_f32_e32 v177, v59, v153
	v_mul_f32_e32 v178, v60, v154
	v_mul_f32_e32 v179, v61, v155
	v_add_u32_e32 v201, 0x2000, v20
	ds_write2_b32 v20, v172, v176 offset1:1
	ds_write2_b32 v20, v173, v177 offset0:2 offset1:3
	ds_write2_b32 v201, v174, v178 offset1:1
	ds_write2_b32 v201, v175, v179 offset0:2 offset1:3
	v_add_u32_e32 v20, v48, v130
	v_mul_f32_e32 v67, v65, v66
	v_mul_f32_e32 v69, v65, v68
	v_mul_f32_e32 v63, v65, v62
	v_mul_f32_e32 v65, v65, v64
	ds_write_b128 v20, v[66:69] offset:40960
	ds_write_b128 v20, v[62:65] offset:40976
	s_and_saveexec_b64 s[2:3], s[0:1]
	s_cbranch_execz .LBB0_195
	v_add_co_u32_e32 v20, vcc, 0x15d01000, v30
	s_nop 1
	v_addc_co_u32_e32 v21, vcc, 0, v31, vcc
	global_store_dword v[20:21], v22, off offset:1024
	s_branch .LBB0_195

.Lrw_scan_loop:
	s_and_b32 s2, s8, 1
	s_mul_i32 s3, s2, 0xe000
	s_lshl_b32 s2, s2, 12
	v_add_u32_e32 v195, s3, v103
	v_add_u32_e32 v33, s3, v38
	v_add_u32_e32 v196, s3, v75
	v_add_u32_e32 v36, s3, v37
	v_add_u32_e32 v102, s2, v76
	ds_read_b128 v[140:143], v195 offset:0
	ds_read_b128 v[152:155], v195 offset:8192
	ds_read_b128 v[176:179], v195 offset:16384
	ds_read_b128 v[84:87], v195 offset:32768
	ds_read_b64 v[4:5], v196 offset:0
	ds_read_b64 v[6:7], v36 offset:0
	ds_read_b128 v[144:147], v195 offset:256
	ds_read_b128 v[156:159], v195 offset:8448
	ds_read_b128 v[180:183], v195 offset:16640
	ds_read_b128 v[88:91], v195 offset:33024
	ds_read_b64 v[8:9], v196 offset:512
	ds_read_b64 v[10:11], v36 offset:512
	s_waitcnt lgkmcnt(6)
	v_pk_mul_f32 v[46:47], v[24:25], v[140:141] op_sel_hi:[0,1]
	v_pk_mul_f32 v[34:35], v[20:21], v[140:141] op_sel_hi:[0,1]
	v_pk_fma_f32 v[46:47], v[24:25], v[142:143], v[46:47] op_sel:[1,0,0] op_sel_hi:[1,1,1]
	v_pk_fma_f32 v[34:35], v[20:21], v[142:143], v[34:35] op_sel:[1,0,0] op_sel_hi:[1,1,1]
	v_pk_fma_f32 v[46:47], v[26:27], v[152:153], v[46:47] op_sel_hi:[0,1,1]
	v_pk_fma_f32 v[34:35], v[22:23], v[152:153], v[34:35] op_sel_hi:[0,1,1]
	v_pk_fma_f32 v[46:47], v[26:27], v[154:155], v[46:47] op_sel:[1,0,0] op_sel_hi:[1,1,1]
	v_pk_fma_f32 v[34:35], v[22:23], v[154:155], v[34:35] op_sel:[1,0,0] op_sel_hi:[1,1,1]
	v_pk_fma_f32 v[20:21], v[176:177], v[4:5], v[20:21] op_sel_hi:[1,0,1]
	v_add_f32_dpp v28, v46, v34 row_half_mirror row_mask:0xf bank_mask:0xf
	v_add_f32_dpp v32, v47, v35 row_half_mirror row_mask:0xf bank_mask:0xf
	v_pk_fma_f32 v[22:23], v[178:179], v[4:5], v[22:23] op_sel_hi:[1,0,1]
	v_add_f32_dpp v28, v28, v28 row_ror:8 row_mask:0xf bank_mask:0xf
	v_add_f32_dpp v32, v32, v32 row_ror:8 row_mask:0xf bank_mask:0xf
	v_pk_fma_f32 v[24:25], v[176:177], v[6:7], v[24:25] op_sel_hi:[1,0,1]
	v_add_f32_dpp v28, v28, v28 quad_perm:[1,0,3,2] row_mask:0xf bank_mask:0xf
	v_add_f32_dpp v32, v32, v32 quad_perm:[1,0,3,2] row_mask:0xf bank_mask:0xf
	v_pk_fma_f32 v[26:27], v[178:179], v[6:7], v[26:27] op_sel_hi:[1,0,1]
	v_add_f32_dpp v28, v28, v28 quad_perm:[2,3,0,1] row_mask:0xf bank_mask:0xf
	v_add_f32_dpp v32, v32, v32 quad_perm:[2,3,0,1] row_mask:0xf bank_mask:0xf
	v_add_f32_e32 v39, v32, v5
	v_mov_b32_dpp v30, v28 row_half_mirror row_mask:0xf bank_mask:0xf
	v_pk_fma_f32 v[20:21], v[84:85], v[28:29], v[20:21] op_sel_hi:[1,0,1] neg_lo:[0,1,0] neg_hi:[0,1,0]
	v_pk_fma_f32 v[22:23], v[86:87], v[28:29], v[22:23] op_sel_hi:[1,0,1] neg_lo:[0,1,0] neg_hi:[0,1,0]
	v_pk_fma_f32 v[24:25], v[84:85], v[30:31], v[24:25] op_sel_hi:[1,0,1] neg_lo:[0,1,0] neg_hi:[0,1,0]
	v_pk_fma_f32 v[26:27], v[86:87], v[30:31], v[26:27] op_sel_hi:[1,0,1] neg_lo:[0,1,0] neg_hi:[0,1,0]
	ds_write_b32 v102, v39 offset:0
	ds_read_b128 v[140:143], v195 offset:512
	ds_read_b128 v[152:155], v195 offset:8704
	ds_read_b128 v[176:179], v195 offset:16896
	ds_read_b128 v[84:87], v195 offset:33280
	ds_read_b64 v[4:5], v196 offset:1024
	ds_read_b64 v[6:7], v36 offset:1024
	s_waitcnt lgkmcnt(7)
	v_pk_mul_f32 v[46:47], v[24:25], v[144:145] op_sel_hi:[0,1]
	v_pk_mul_f32 v[34:35], v[20:21], v[144:145] op_sel_hi:[0,1]
	v_pk_fma_f32 v[46:47], v[24:25], v[146:147], v[46:47] op_sel:[1,0,0] op_sel_hi:[1,1,1]
	v_pk_fma_f32 v[34:35], v[20:21], v[146:147], v[34:35] op_sel:[1,0,0] op_sel_hi:[1,1,1]
	v_pk_fma_f32 v[46:47], v[26:27], v[156:157], v[46:47] op_sel_hi:[0,1,1]
	v_pk_fma_f32 v[34:35], v[22:23], v[156:157], v[34:35] op_sel_hi:[0,1,1]
	v_pk_fma_f32 v[46:47], v[26:27], v[158:159], v[46:47] op_sel:[1,0,0] op_sel_hi:[1,1,1]
	v_pk_fma_f32 v[34:35], v[22:23], v[158:159], v[34:35] op_sel:[1,0,0] op_sel_hi:[1,1,1]
	v_pk_fma_f32 v[20:21], v[180:181], v[8:9], v[20:21] op_sel_hi:[1,0,1]
	v_add_f32_dpp v28, v46, v34 row_half_mirror row_mask:0xf bank_mask:0xf
	v_add_f32_dpp v32, v47, v35 row_half_mirror row_mask:0xf bank_mask:0xf
	v_pk_fma_f32 v[22:23], v[182:183], v[8:9], v[22:23] op_sel_hi:[1,0,1]
	v_add_f32_dpp v28, v28, v28 row_ror:8 row_mask:0xf bank_mask:0xf
	v_add_f32_dpp v32, v32, v32 row_ror:8 row_mask:0xf bank_mask:0xf
	v_pk_fma_f32 v[24:25], v[180:181], v[10:11], v[24:25] op_sel_hi:[1,0,1]
	v_add_f32_dpp v28, v28, v28 quad_perm:[1,0,3,2] row_mask:0xf bank_mask:0xf
	v_add_f32_dpp v32, v32, v32 quad_perm:[1,0,3,2] row_mask:0xf bank_mask:0xf
	v_pk_fma_f32 v[26:27], v[182:183], v[10:11], v[26:27] op_sel_hi:[1,0,1]
	v_add_f32_dpp v28, v28, v28 quad_perm:[2,3,0,1] row_mask:0xf bank_mask:0xf
	v_add_f32_dpp v32, v32, v32 quad_perm:[2,3,0,1] row_mask:0xf bank_mask:0xf
	v_add_f32_e32 v39, v32, v9
	v_mov_b32_dpp v30, v28 row_half_mirror row_mask:0xf bank_mask:0xf
	v_pk_fma_f32 v[20:21], v[88:89], v[28:29], v[20:21] op_sel_hi:[1,0,1] neg_lo:[0,1,0] neg_hi:[0,1,0]
	v_pk_fma_f32 v[22:23], v[90:91], v[28:29], v[22:23] op_sel_hi:[1,0,1] neg_lo:[0,1,0] neg_hi:[0,1,0]
	v_pk_fma_f32 v[24:25], v[88:89], v[30:31], v[24:25] op_sel_hi:[1,0,1] neg_lo:[0,1,0] neg_hi:[0,1,0]
	v_pk_fma_f32 v[26:27], v[90:91], v[30:31], v[26:27] op_sel_hi:[1,0,1] neg_lo:[0,1,0] neg_hi:[0,1,0]
	ds_write_b32 v102, v39 offset:128
	ds_read_b128 v[144:147], v195 offset:768
	ds_read_b128 v[156:159], v195 offset:8960
	ds_read_b128 v[168:171], v195 offset:25344
	ds_read_b128 v[180:183], v195 offset:17152
	ds_read_b128 v[88:91], v195 offset:33536
	ds_read_b64 v[8:9], v196 offset:1536
	ds_read_b64 v[10:11], v36 offset:1536
	s_waitcnt lgkmcnt(8)
	v_pk_mul_f32 v[46:47], v[24:25], v[140:141] op_sel_hi:[0,1]
	v_pk_mul_f32 v[34:35], v[20:21], v[140:141] op_sel_hi:[0,1]
	v_pk_fma_f32 v[46:47], v[24:25], v[142:143], v[46:47] op_sel:[1,0,0] op_sel_hi:[1,1,1]
	v_pk_fma_f32 v[34:35], v[20:21], v[142:143], v[34:35] op_sel:[1,0,0] op_sel_hi:[1,1,1]
	v_pk_fma_f32 v[46:47], v[26:27], v[152:153], v[46:47] op_sel_hi:[0,1,1]
	v_pk_fma_f32 v[34:35], v[22:23], v[152:153], v[34:35] op_sel_hi:[0,1,1]
	v_pk_fma_f32 v[46:47], v[26:27], v[154:155], v[46:47] op_sel:[1,0,0] op_sel_hi:[1,1,1]
	v_pk_fma_f32 v[34:35], v[22:23], v[154:155], v[34:35] op_sel:[1,0,0] op_sel_hi:[1,1,1]
	v_pk_fma_f32 v[20:21], v[176:177], v[4:5], v[20:21] op_sel_hi:[1,0,1]
	v_add_f32_dpp v28, v46, v34 row_half_mirror row_mask:0xf bank_mask:0xf
	v_add_f32_dpp v32, v47, v35 row_half_mirror row_mask:0xf bank_mask:0xf
	v_pk_fma_f32 v[22:23], v[178:179], v[4:5], v[22:23] op_sel_hi:[1,0,1]
	v_add_f32_dpp v28, v28, v28 row_ror:8 row_mask:0xf bank_mask:0xf
	v_add_f32_dpp v32, v32, v32 row_ror:8 row_mask:0xf bank_mask:0xf
	v_pk_fma_f32 v[24:25], v[176:177], v[6:7], v[24:25] op_sel_hi:[1,0,1]
	v_add_f32_dpp v28, v28, v28 quad_perm:[1,0,3,2] row_mask:0xf bank_mask:0xf
	v_add_f32_dpp v32, v32, v32 quad_perm:[1,0,3,2] row_mask:0xf bank_mask:0xf
	v_pk_fma_f32 v[26:27], v[178:179], v[6:7], v[26:27] op_sel_hi:[1,0,1]
	v_add_f32_dpp v28, v28, v28 quad_perm:[2,3,0,1] row_mask:0xf bank_mask:0xf
	v_add_f32_dpp v32, v32, v32 quad_perm:[2,3,0,1] row_mask:0xf bank_mask:0xf
	v_add_f32_e32 v39, v32, v5
	v_mov_b32_dpp v30, v28 row_half_mirror row_mask:0xf bank_mask:0xf
	v_pk_fma_f32 v[20:21], v[84:85], v[28:29], v[20:21] op_sel_hi:[1,0,1] neg_lo:[0,1,0] neg_hi:[0,1,0]
	v_pk_fma_f32 v[22:23], v[86:87], v[28:29], v[22:23] op_sel_hi:[1,0,1] neg_lo:[0,1,0] neg_hi:[0,1,0]
	v_pk_fma_f32 v[24:25], v[84:85], v[30:31], v[24:25] op_sel_hi:[1,0,1] neg_lo:[0,1,0] neg_hi:[0,1,0]
	v_pk_fma_f32 v[26:27], v[86:87], v[30:31], v[26:27] op_sel_hi:[1,0,1] neg_lo:[0,1,0] neg_hi:[0,1,0]
	ds_write_b32 v102, v39 offset:256
	ds_read_b128 v[140:143], v195 offset:1024
	ds_read_b128 v[152:155], v195 offset:9216
	ds_read_b128 v[176:179], v195 offset:17408
	ds_read_b128 v[84:87], v195 offset:33792
	ds_read_b64 v[4:5], v196 offset:2048
	ds_read_b64 v[6:7], v36 offset:2048
	s_waitcnt lgkmcnt(7)
	v_pk_mul_f32 v[46:47], v[24:25], v[144:145] op_sel_hi:[0,1]
	v_pk_mul_f32 v[34:35], v[20:21], v[144:145] op_sel_hi:[0,1]
	v_pk_fma_f32 v[46:47], v[24:25], v[146:147], v[46:47] op_sel:[1,0,0] op_sel_hi:[1,1,1]
	v_pk_fma_f32 v[34:35], v[20:21], v[146:147], v[34:35] op_sel:[1,0,0] op_sel_hi:[1,1,1]
	v_pk_fma_f32 v[46:47], v[26:27], v[156:157], v[46:47] op_sel_hi:[0,1,1]
	v_pk_fma_f32 v[34:35], v[22:23], v[156:157], v[34:35] op_sel_hi:[0,1,1]
	v_pk_fma_f32 v[46:47], v[26:27], v[158:159], v[46:47] op_sel:[1,0,0] op_sel_hi:[1,1,1]
	v_pk_fma_f32 v[34:35], v[22:23], v[158:159], v[34:35] op_sel:[1,0,0] op_sel_hi:[1,1,1]
	v_pk_mul_f32 v[20:21], v[20:21], v[168:169]
	v_add_f32_dpp v28, v46, v34 row_half_mirror row_mask:0xf bank_mask:0xf
	v_add_f32_dpp v32, v47, v35 row_half_mirror row_mask:0xf bank_mask:0xf
	v_pk_mul_f32 v[22:23], v[22:23], v[170:171]
	v_add_f32_dpp v28, v28, v28 row_ror:8 row_mask:0xf bank_mask:0xf
	v_add_f32_dpp v32, v32, v32 row_ror:8 row_mask:0xf bank_mask:0xf
	v_pk_mul_f32 v[24:25], v[24:25], v[168:169]
	v_add_f32_dpp v28, v28, v28 quad_perm:[1,0,3,2] row_mask:0xf bank_mask:0xf
	v_add_f32_dpp v32, v32, v32 quad_perm:[1,0,3,2] row_mask:0xf bank_mask:0xf
	v_pk_mul_f32 v[26:27], v[26:27], v[170:171]
	v_add_f32_dpp v28, v28, v28 quad_perm:[2,3,0,1] row_mask:0xf bank_mask:0xf
	v_add_f32_dpp v32, v32, v32 quad_perm:[2,3,0,1] row_mask:0xf bank_mask:0xf
	v_pk_fma_f32 v[20:21], v[180:181], v[8:9], v[20:21] op_sel_hi:[1,0,1]
	v_mov_b32_dpp v30, v28 row_half_mirror row_mask:0xf bank_mask:0xf
	v_pk_fma_f32 v[22:23], v[182:183], v[8:9], v[22:23] op_sel_hi:[1,0,1]
	v_pk_fma_f32 v[24:25], v[180:181], v[10:11], v[24:25] op_sel_hi:[1,0,1]
	v_pk_fma_f32 v[26:27], v[182:183], v[10:11], v[26:27] op_sel_hi:[1,0,1]
	v_pk_fma_f32 v[20:21], v[88:89], v[28:29], v[20:21] op_sel_hi:[1,0,1] neg_lo:[0,1,0] neg_hi:[0,1,0]
	v_pk_fma_f32 v[22:23], v[90:91], v[28:29], v[22:23] op_sel_hi:[1,0,1] neg_lo:[0,1,0] neg_hi:[0,1,0]
	v_pk_fma_f32 v[24:25], v[88:89], v[30:31], v[24:25] op_sel_hi:[1,0,1] neg_lo:[0,1,0] neg_hi:[0,1,0]
	v_pk_fma_f32 v[26:27], v[90:91], v[30:31], v[26:27] op_sel_hi:[1,0,1] neg_lo:[0,1,0] neg_hi:[0,1,0]
	v_add_f32_e32 v39, v32, v9
	ds_write_b32 v102, v39 offset:384
	ds_read_b128 v[144:147], v195 offset:1280
	ds_read_b128 v[156:159], v195 offset:9472
	ds_read_b128 v[180:183], v195 offset:17664
	ds_read_b128 v[88:91], v195 offset:34048
	ds_read_b64 v[8:9], v196 offset:2560
	ds_read_b64 v[10:11], v36 offset:2560
	s_waitcnt lgkmcnt(7)
	v_pk_mul_f32 v[46:47], v[24:25], v[140:141] op_sel_hi:[0,1]
	v_pk_mul_f32 v[34:35], v[20:21], v[140:141] op_sel_hi:[0,1]
	v_pk_fma_f32 v[46:47], v[24:25], v[142:143], v[46:47] op_sel:[1,0,0] op_sel_hi:[1,1,1]
	v_pk_fma_f32 v[34:35], v[20:21], v[142:143], v[34:35] op_sel:[1,0,0] op_sel_hi:[1,1,1]
	v_pk_fma_f32 v[46:47], v[26:27], v[152:153], v[46:47] op_sel_hi:[0,1,1]
	v_pk_fma_f32 v[34:35], v[22:23], v[152:153], v[34:35] op_sel_hi:[0,1,1]
	v_pk_fma_f32 v[46:47], v[26:27], v[154:155], v[46:47] op_sel:[1,0,0] op_sel_hi:[1,1,1]
	v_pk_fma_f32 v[34:35], v[22:23], v[154:155], v[34:35] op_sel:[1,0,0] op_sel_hi:[1,1,1]
	v_pk_fma_f32 v[20:21], v[176:177], v[4:5], v[20:21] op_sel_hi:[1,0,1]
	v_add_f32_dpp v28, v46, v34 row_half_mirror row_mask:0xf bank_mask:0xf
	v_add_f32_dpp v32, v47, v35 row_half_mirror row_mask:0xf bank_mask:0xf
	v_pk_fma_f32 v[22:23], v[178:179], v[4:5], v[22:23] op_sel_hi:[1,0,1]
	v_add_f32_dpp v28, v28, v28 row_ror:8 row_mask:0xf bank_mask:0xf
	v_add_f32_dpp v32, v32, v32 row_ror:8 row_mask:0xf bank_mask:0xf
	v_pk_fma_f32 v[24:25], v[176:177], v[6:7], v[24:25] op_sel_hi:[1,0,1]
	v_add_f32_dpp v28, v28, v28 quad_perm:[1,0,3,2] row_mask:0xf bank_mask:0xf
	v_add_f32_dpp v32, v32, v32 quad_perm:[1,0,3,2] row_mask:0xf bank_mask:0xf
	v_pk_fma_f32 v[26:27], v[178:179], v[6:7], v[26:27] op_sel_hi:[1,0,1]
	v_add_f32_dpp v28, v28, v28 quad_perm:[2,3,0,1] row_mask:0xf bank_mask:0xf
	v_add_f32_dpp v32, v32, v32 quad_perm:[2,3,0,1] row_mask:0xf bank_mask:0xf
	v_add_f32_e32 v39, v32, v5
	v_mov_b32_dpp v30, v28 row_half_mirror row_mask:0xf bank_mask:0xf
	v_pk_fma_f32 v[20:21], v[84:85], v[28:29], v[20:21] op_sel_hi:[1,0,1] neg_lo:[0,1,0] neg_hi:[0,1,0]
	v_pk_fma_f32 v[22:23], v[86:87], v[28:29], v[22:23] op_sel_hi:[1,0,1] neg_lo:[0,1,0] neg_hi:[0,1,0]
	v_pk_fma_f32 v[24:25], v[84:85], v[30:31], v[24:25] op_sel_hi:[1,0,1] neg_lo:[0,1,0] neg_hi:[0,1,0]
	v_pk_fma_f32 v[26:27], v[86:87], v[30:31], v[26:27] op_sel_hi:[1,0,1] neg_lo:[0,1,0] neg_hi:[0,1,0]
	ds_write_b32 v102, v39 offset:512
	ds_read_b128 v[140:143], v195 offset:1536
	ds_read_b128 v[152:155], v195 offset:9728
	ds_read_b128 v[176:179], v195 offset:17920
	ds_read_b128 v[84:87], v195 offset:34304
	ds_read_b64 v[4:5], v196 offset:3072
	ds_read_b64 v[6:7], v36 offset:3072
	s_waitcnt lgkmcnt(7)
	v_pk_mul_f32 v[46:47], v[24:25], v[144:145] op_sel_hi:[0,1]
	v_pk_mul_f32 v[34:35], v[20:21], v[144:145] op_sel_hi:[0,1]
	v_pk_fma_f32 v[46:47], v[24:25], v[146:147], v[46:47] op_sel:[1,0,0] op_sel_hi:[1,1,1]
	v_pk_fma_f32 v[34:35], v[20:21], v[146:147], v[34:35] op_sel:[1,0,0] op_sel_hi:[1,1,1]
	v_pk_fma_f32 v[46:47], v[26:27], v[156:157], v[46:47] op_sel_hi:[0,1,1]
	v_pk_fma_f32 v[34:35], v[22:23], v[156:157], v[34:35] op_sel_hi:[0,1,1]
	v_pk_fma_f32 v[46:47], v[26:27], v[158:159], v[46:47] op_sel:[1,0,0] op_sel_hi:[1,1,1]
	v_pk_fma_f32 v[34:35], v[22:23], v[158:159], v[34:35] op_sel:[1,0,0] op_sel_hi:[1,1,1]
	v_pk_fma_f32 v[20:21], v[180:181], v[8:9], v[20:21] op_sel_hi:[1,0,1]
	v_add_f32_dpp v28, v46, v34 row_half_mirror row_mask:0xf bank_mask:0xf
	v_add_f32_dpp v32, v47, v35 row_half_mirror row_mask:0xf bank_mask:0xf
	v_pk_fma_f32 v[22:23], v[182:183], v[8:9], v[22:23] op_sel_hi:[1,0,1]
	v_add_f32_dpp v28, v28, v28 row_ror:8 row_mask:0xf bank_mask:0xf
	v_add_f32_dpp v32, v32, v32 row_ror:8 row_mask:0xf bank_mask:0xf
	v_pk_fma_f32 v[24:25], v[180:181], v[10:11], v[24:25] op_sel_hi:[1,0,1]
	v_add_f32_dpp v28, v28, v28 quad_perm:[1,0,3,2] row_mask:0xf bank_mask:0xf
	v_add_f32_dpp v32, v32, v32 quad_perm:[1,0,3,2] row_mask:0xf bank_mask:0xf
	v_pk_fma_f32 v[26:27], v[182:183], v[10:11], v[26:27] op_sel_hi:[1,0,1]
	v_add_f32_dpp v28, v28, v28 quad_perm:[2,3,0,1] row_mask:0xf bank_mask:0xf
	v_add_f32_dpp v32, v32, v32 quad_perm:[2,3,0,1] row_mask:0xf bank_mask:0xf
	v_add_f32_e32 v39, v32, v9
	v_mov_b32_dpp v30, v28 row_half_mirror row_mask:0xf bank_mask:0xf
	v_pk_fma_f32 v[20:21], v[88:89], v[28:29], v[20:21] op_sel_hi:[1,0,1] neg_lo:[0,1,0] neg_hi:[0,1,0]
	v_pk_fma_f32 v[22:23], v[90:91], v[28:29], v[22:23] op_sel_hi:[1,0,1] neg_lo:[0,1,0] neg_hi:[0,1,0]
	v_pk_fma_f32 v[24:25], v[88:89], v[30:31], v[24:25] op_sel_hi:[1,0,1] neg_lo:[0,1,0] neg_hi:[0,1,0]
	v_pk_fma_f32 v[26:27], v[90:91], v[30:31], v[26:27] op_sel_hi:[1,0,1] neg_lo:[0,1,0] neg_hi:[0,1,0]
	ds_write_b32 v102, v39 offset:640
	ds_read_b128 v[144:147], v195 offset:1792
	ds_read_b128 v[156:159], v195 offset:9984
	ds_read_b128 v[168:171], v195 offset:26368
	ds_read_b128 v[180:183], v195 offset:18176
	ds_read_b128 v[88:91], v195 offset:34560
	ds_read_b64 v[8:9], v196 offset:3584
	ds_read_b64 v[10:11], v36 offset:3584
	s_waitcnt lgkmcnt(8)
	v_pk_mul_f32 v[46:47], v[24:25], v[140:141] op_sel_hi:[0,1]
	v_pk_mul_f32 v[34:35], v[20:21], v[140:141] op_sel_hi:[0,1]
	v_pk_fma_f32 v[46:47], v[24:25], v[142:143], v[46:47] op_sel:[1,0,0] op_sel_hi:[1,1,1]
	v_pk_fma_f32 v[34:35], v[20:21], v[142:143], v[34:35] op_sel:[1,0,0] op_sel_hi:[1,1,1]
	v_pk_fma_f32 v[46:47], v[26:27], v[152:153], v[46:47] op_sel_hi:[0,1,1]
	v_pk_fma_f32 v[34:35], v[22:23], v[152:153], v[34:35] op_sel_hi:[0,1,1]
	v_pk_fma_f32 v[46:47], v[26:27], v[154:155], v[46:47] op_sel:[1,0,0] op_sel_hi:[1,1,1]
	v_pk_fma_f32 v[34:35], v[22:23], v[154:155], v[34:35] op_sel:[1,0,0] op_sel_hi:[1,1,1]
	v_pk_fma_f32 v[20:21], v[176:177], v[4:5], v[20:21] op_sel_hi:[1,0,1]
	v_add_f32_dpp v28, v46, v34 row_half_mirror row_mask:0xf bank_mask:0xf
	v_add_f32_dpp v32, v47, v35 row_half_mirror row_mask:0xf bank_mask:0xf
	v_pk_fma_f32 v[22:23], v[178:179], v[4:5], v[22:23] op_sel_hi:[1,0,1]
	v_add_f32_dpp v28, v28, v28 row_ror:8 row_mask:0xf bank_mask:0xf
	v_add_f32_dpp v32, v32, v32 row_ror:8 row_mask:0xf bank_mask:0xf
	v_pk_fma_f32 v[24:25], v[176:177], v[6:7], v[24:25] op_sel_hi:[1,0,1]
	v_add_f32_dpp v28, v28, v28 quad_perm:[1,0,3,2] row_mask:0xf bank_mask:0xf
	v_add_f32_dpp v32, v32, v32 quad_perm:[1,0,3,2] row_mask:0xf bank_mask:0xf
	v_pk_fma_f32 v[26:27], v[178:179], v[6:7], v[26:27] op_sel_hi:[1,0,1]
	v_add_f32_dpp v28, v28, v28 quad_perm:[2,3,0,1] row_mask:0xf bank_mask:0xf
	v_add_f32_dpp v32, v32, v32 quad_perm:[2,3,0,1] row_mask:0xf bank_mask:0xf
	v_add_f32_e32 v39, v32, v5
	v_mov_b32_dpp v30, v28 row_half_mirror row_mask:0xf bank_mask:0xf
	v_pk_fma_f32 v[20:21], v[84:85], v[28:29], v[20:21] op_sel_hi:[1,0,1] neg_lo:[0,1,0] neg_hi:[0,1,0]
	v_pk_fma_f32 v[22:23], v[86:87], v[28:29], v[22:23] op_sel_hi:[1,0,1] neg_lo:[0,1,0] neg_hi:[0,1,0]
	v_pk_fma_f32 v[24:25], v[84:85], v[30:31], v[24:25] op_sel_hi:[1,0,1] neg_lo:[0,1,0] neg_hi:[0,1,0]
	v_pk_fma_f32 v[26:27], v[86:87], v[30:31], v[26:27] op_sel_hi:[1,0,1] neg_lo:[0,1,0] neg_hi:[0,1,0]
	ds_write_b32 v102, v39 offset:768
	ds_read_b128 v[140:143], v195 offset:2048
	ds_read_b128 v[152:155], v195 offset:10240
	ds_read_b128 v[176:179], v195 offset:18432
	ds_read_b128 v[84:87], v195 offset:34816
	ds_read_b64 v[4:5], v196 offset:4096
	ds_read_b64 v[6:7], v36 offset:4096
	s_waitcnt lgkmcnt(7)
	v_pk_mul_f32 v[46:47], v[24:25], v[144:145] op_sel_hi:[0,1]
	v_pk_mul_f32 v[34:35], v[20:21], v[144:145] op_sel_hi:[0,1]
	v_pk_fma_f32 v[46:47], v[24:25], v[146:147], v[46:47] op_sel:[1,0,0] op_sel_hi:[1,1,1]
	v_pk_fma_f32 v[34:35], v[20:21], v[146:147], v[34:35] op_sel:[1,0,0] op_sel_hi:[1,1,1]
	v_pk_fma_f32 v[46:47], v[26:27], v[156:157], v[46:47] op_sel_hi:[0,1,1]
	v_pk_fma_f32 v[34:35], v[22:23], v[156:157], v[34:35] op_sel_hi:[0,1,1]
	v_pk_fma_f32 v[46:47], v[26:27], v[158:159], v[46:47] op_sel:[1,0,0] op_sel_hi:[1,1,1]
	v_pk_fma_f32 v[34:35], v[22:23], v[158:159], v[34:35] op_sel:[1,0,0] op_sel_hi:[1,1,1]
	v_pk_mul_f32 v[20:21], v[20:21], v[168:169]
	v_add_f32_dpp v28, v46, v34 row_half_mirror row_mask:0xf bank_mask:0xf
	v_add_f32_dpp v32, v47, v35 row_half_mirror row_mask:0xf bank_mask:0xf
	v_pk_mul_f32 v[22:23], v[22:23], v[170:171]
	v_add_f32_dpp v28, v28, v28 row_ror:8 row_mask:0xf bank_mask:0xf
	v_add_f32_dpp v32, v32, v32 row_ror:8 row_mask:0xf bank_mask:0xf
	v_pk_mul_f32 v[24:25], v[24:25], v[168:169]
	v_add_f32_dpp v28, v28, v28 quad_perm:[1,0,3,2] row_mask:0xf bank_mask:0xf
	v_add_f32_dpp v32, v32, v32 quad_perm:[1,0,3,2] row_mask:0xf bank_mask:0xf
	v_pk_mul_f32 v[26:27], v[26:27], v[170:171]
	v_add_f32_dpp v28, v28, v28 quad_perm:[2,3,0,1] row_mask:0xf bank_mask:0xf
	v_add_f32_dpp v32, v32, v32 quad_perm:[2,3,0,1] row_mask:0xf bank_mask:0xf
	v_pk_fma_f32 v[20:21], v[180:181], v[8:9], v[20:21] op_sel_hi:[1,0,1]
	v_mov_b32_dpp v30, v28 row_half_mirror row_mask:0xf bank_mask:0xf
	v_pk_fma_f32 v[22:23], v[182:183], v[8:9], v[22:23] op_sel_hi:[1,0,1]
	v_pk_fma_f32 v[24:25], v[180:181], v[10:11], v[24:25] op_sel_hi:[1,0,1]
	v_pk_fma_f32 v[26:27], v[182:183], v[10:11], v[26:27] op_sel_hi:[1,0,1]
	v_pk_fma_f32 v[20:21], v[88:89], v[28:29], v[20:21] op_sel_hi:[1,0,1] neg_lo:[0,1,0] neg_hi:[0,1,0]
	v_pk_fma_f32 v[22:23], v[90:91], v[28:29], v[22:23] op_sel_hi:[1,0,1] neg_lo:[0,1,0] neg_hi:[0,1,0]
	v_pk_fma_f32 v[24:25], v[88:89], v[30:31], v[24:25] op_sel_hi:[1,0,1] neg_lo:[0,1,0] neg_hi:[0,1,0]
	v_pk_fma_f32 v[26:27], v[90:91], v[30:31], v[26:27] op_sel_hi:[1,0,1] neg_lo:[0,1,0] neg_hi:[0,1,0]
	v_add_f32_e32 v39, v32, v9
	ds_write_b32 v102, v39 offset:896
	ds_read_b128 v[144:147], v195 offset:2304
	ds_read_b128 v[156:159], v195 offset:10496
	ds_read_b128 v[180:183], v195 offset:18688
	ds_read_b128 v[88:91], v195 offset:35072
	ds_read_b64 v[8:9], v196 offset:4608
	ds_read_b64 v[10:11], v36 offset:4608
	s_waitcnt lgkmcnt(7)
	v_pk_mul_f32 v[46:47], v[24:25], v[140:141] op_sel_hi:[0,1]
	v_pk_mul_f32 v[34:35], v[20:21], v[140:141] op_sel_hi:[0,1]
	v_pk_fma_f32 v[46:47], v[24:25], v[142:143], v[46:47] op_sel:[1,0,0] op_sel_hi:[1,1,1]
	v_pk_fma_f32 v[34:35], v[20:21], v[142:143], v[34:35] op_sel:[1,0,0] op_sel_hi:[1,1,1]
	v_pk_fma_f32 v[46:47], v[26:27], v[152:153], v[46:47] op_sel_hi:[0,1,1]
	v_pk_fma_f32 v[34:35], v[22:23], v[152:153], v[34:35] op_sel_hi:[0,1,1]
	v_pk_fma_f32 v[46:47], v[26:27], v[154:155], v[46:47] op_sel:[1,0,0] op_sel_hi:[1,1,1]
	v_pk_fma_f32 v[34:35], v[22:23], v[154:155], v[34:35] op_sel:[1,0,0] op_sel_hi:[1,1,1]
	v_pk_fma_f32 v[20:21], v[176:177], v[4:5], v[20:21] op_sel_hi:[1,0,1]
	v_add_f32_dpp v28, v46, v34 row_half_mirror row_mask:0xf bank_mask:0xf
	v_add_f32_dpp v32, v47, v35 row_half_mirror row_mask:0xf bank_mask:0xf
	v_pk_fma_f32 v[22:23], v[178:179], v[4:5], v[22:23] op_sel_hi:[1,0,1]
	v_add_f32_dpp v28, v28, v28 row_ror:8 row_mask:0xf bank_mask:0xf
	v_add_f32_dpp v32, v32, v32 row_ror:8 row_mask:0xf bank_mask:0xf
	v_pk_fma_f32 v[24:25], v[176:177], v[6:7], v[24:25] op_sel_hi:[1,0,1]
	v_add_f32_dpp v28, v28, v28 quad_perm:[1,0,3,2] row_mask:0xf bank_mask:0xf
	v_add_f32_dpp v32, v32, v32 quad_perm:[1,0,3,2] row_mask:0xf bank_mask:0xf
	v_pk_fma_f32 v[26:27], v[178:179], v[6:7], v[26:27] op_sel_hi:[1,0,1]
	v_add_f32_dpp v28, v28, v28 quad_perm:[2,3,0,1] row_mask:0xf bank_mask:0xf
	v_add_f32_dpp v32, v32, v32 quad_perm:[2,3,0,1] row_mask:0xf bank_mask:0xf
	v_add_f32_e32 v39, v32, v5
	v_mov_b32_dpp v30, v28 row_half_mirror row_mask:0xf bank_mask:0xf
	v_pk_fma_f32 v[20:21], v[84:85], v[28:29], v[20:21] op_sel_hi:[1,0,1] neg_lo:[0,1,0] neg_hi:[0,1,0]
	v_pk_fma_f32 v[22:23], v[86:87], v[28:29], v[22:23] op_sel_hi:[1,0,1] neg_lo:[0,1,0] neg_hi:[0,1,0]
	v_pk_fma_f32 v[24:25], v[84:85], v[30:31], v[24:25] op_sel_hi:[1,0,1] neg_lo:[0,1,0] neg_hi:[0,1,0]
	v_pk_fma_f32 v[26:27], v[86:87], v[30:31], v[26:27] op_sel_hi:[1,0,1] neg_lo:[0,1,0] neg_hi:[0,1,0]
	ds_write_b32 v102, v39 offset:1024
	ds_read_b128 v[140:143], v195 offset:2560
	ds_read_b128 v[152:155], v195 offset:10752
	ds_read_b128 v[176:179], v195 offset:18944
	ds_read_b128 v[84:87], v195 offset:35328
	ds_read_b64 v[4:5], v196 offset:5120
	ds_read_b64 v[6:7], v36 offset:5120
	s_waitcnt lgkmcnt(7)
	v_pk_mul_f32 v[46:47], v[24:25], v[144:145] op_sel_hi:[0,1]
	v_pk_mul_f32 v[34:35], v[20:21], v[144:145] op_sel_hi:[0,1]
	v_pk_fma_f32 v[46:47], v[24:25], v[146:147], v[46:47] op_sel:[1,0,0] op_sel_hi:[1,1,1]
	v_pk_fma_f32 v[34:35], v[20:21], v[146:147], v[34:35] op_sel:[1,0,0] op_sel_hi:[1,1,1]
	v_pk_fma_f32 v[46:47], v[26:27], v[156:157], v[46:47] op_sel_hi:[0,1,1]
	v_pk_fma_f32 v[34:35], v[22:23], v[156:157], v[34:35] op_sel_hi:[0,1,1]
	v_pk_fma_f32 v[46:47], v[26:27], v[158:159], v[46:47] op_sel:[1,0,0] op_sel_hi:[1,1,1]
	v_pk_fma_f32 v[34:35], v[22:23], v[158:159], v[34:35] op_sel:[1,0,0] op_sel_hi:[1,1,1]
	v_pk_fma_f32 v[20:21], v[180:181], v[8:9], v[20:21] op_sel_hi:[1,0,1]
	v_add_f32_dpp v28, v46, v34 row_half_mirror row_mask:0xf bank_mask:0xf
	v_add_f32_dpp v32, v47, v35 row_half_mirror row_mask:0xf bank_mask:0xf
	v_pk_fma_f32 v[22:23], v[182:183], v[8:9], v[22:23] op_sel_hi:[1,0,1]
	v_add_f32_dpp v28, v28, v28 row_ror:8 row_mask:0xf bank_mask:0xf
	v_add_f32_dpp v32, v32, v32 row_ror:8 row_mask:0xf bank_mask:0xf
	v_pk_fma_f32 v[24:25], v[180:181], v[10:11], v[24:25] op_sel_hi:[1,0,1]
	v_add_f32_dpp v28, v28, v28 quad_perm:[1,0,3,2] row_mask:0xf bank_mask:0xf
	v_add_f32_dpp v32, v32, v32 quad_perm:[1,0,3,2] row_mask:0xf bank_mask:0xf
	v_pk_fma_f32 v[26:27], v[182:183], v[10:11], v[26:27] op_sel_hi:[1,0,1]
	v_add_f32_dpp v28, v28, v28 quad_perm:[2,3,0,1] row_mask:0xf bank_mask:0xf
	v_add_f32_dpp v32, v32, v32 quad_perm:[2,3,0,1] row_mask:0xf bank_mask:0xf
	v_add_f32_e32 v39, v32, v9
	v_mov_b32_dpp v30, v28 row_half_mirror row_mask:0xf bank_mask:0xf
	v_pk_fma_f32 v[20:21], v[88:89], v[28:29], v[20:21] op_sel_hi:[1,0,1] neg_lo:[0,1,0] neg_hi:[0,1,0]
	v_pk_fma_f32 v[22:23], v[90:91], v[28:29], v[22:23] op_sel_hi:[1,0,1] neg_lo:[0,1,0] neg_hi:[0,1,0]
	v_pk_fma_f32 v[24:25], v[88:89], v[30:31], v[24:25] op_sel_hi:[1,0,1] neg_lo:[0,1,0] neg_hi:[0,1,0]
	v_pk_fma_f32 v[26:27], v[90:91], v[30:31], v[26:27] op_sel_hi:[1,0,1] neg_lo:[0,1,0] neg_hi:[0,1,0]
	ds_write_b32 v102, v39 offset:1152
	ds_read_b128 v[144:147], v195 offset:2816
	ds_read_b128 v[156:159], v195 offset:11008
	ds_read_b128 v[168:171], v195 offset:27392
	ds_read_b128 v[180:183], v195 offset:19200
	ds_read_b128 v[88:91], v195 offset:35584
	ds_read_b64 v[8:9], v196 offset:5632
	ds_read_b64 v[10:11], v36 offset:5632
	s_waitcnt lgkmcnt(8)
	v_pk_mul_f32 v[46:47], v[24:25], v[140:141] op_sel_hi:[0,1]
	v_pk_mul_f32 v[34:35], v[20:21], v[140:141] op_sel_hi:[0,1]
	v_pk_fma_f32 v[46:47], v[24:25], v[142:143], v[46:47] op_sel:[1,0,0] op_sel_hi:[1,1,1]
	v_pk_fma_f32 v[34:35], v[20:21], v[142:143], v[34:35] op_sel:[1,0,0] op_sel_hi:[1,1,1]
	v_pk_fma_f32 v[46:47], v[26:27], v[152:153], v[46:47] op_sel_hi:[0,1,1]
	v_pk_fma_f32 v[34:35], v[22:23], v[152:153], v[34:35] op_sel_hi:[0,1,1]
	v_pk_fma_f32 v[46:47], v[26:27], v[154:155], v[46:47] op_sel:[1,0,0] op_sel_hi:[1,1,1]
	v_pk_fma_f32 v[34:35], v[22:23], v[154:155], v[34:35] op_sel:[1,0,0] op_sel_hi:[1,1,1]
	v_pk_fma_f32 v[20:21], v[176:177], v[4:5], v[20:21] op_sel_hi:[1,0,1]
	v_add_f32_dpp v28, v46, v34 row_half_mirror row_mask:0xf bank_mask:0xf
	v_add_f32_dpp v32, v47, v35 row_half_mirror row_mask:0xf bank_mask:0xf
	v_pk_fma_f32 v[22:23], v[178:179], v[4:5], v[22:23] op_sel_hi:[1,0,1]
	v_add_f32_dpp v28, v28, v28 row_ror:8 row_mask:0xf bank_mask:0xf
	v_add_f32_dpp v32, v32, v32 row_ror:8 row_mask:0xf bank_mask:0xf
	v_pk_fma_f32 v[24:25], v[176:177], v[6:7], v[24:25] op_sel_hi:[1,0,1]
	v_add_f32_dpp v28, v28, v28 quad_perm:[1,0,3,2] row_mask:0xf bank_mask:0xf
	v_add_f32_dpp v32, v32, v32 quad_perm:[1,0,3,2] row_mask:0xf bank_mask:0xf
	v_pk_fma_f32 v[26:27], v[178:179], v[6:7], v[26:27] op_sel_hi:[1,0,1]
	v_add_f32_dpp v28, v28, v28 quad_perm:[2,3,0,1] row_mask:0xf bank_mask:0xf
	v_add_f32_dpp v32, v32, v32 quad_perm:[2,3,0,1] row_mask:0xf bank_mask:0xf
	v_add_f32_e32 v39, v32, v5
	v_mov_b32_dpp v30, v28 row_half_mirror row_mask:0xf bank_mask:0xf
	v_pk_fma_f32 v[20:21], v[84:85], v[28:29], v[20:21] op_sel_hi:[1,0,1] neg_lo:[0,1,0] neg_hi:[0,1,0]
	v_pk_fma_f32 v[22:23], v[86:87], v[28:29], v[22:23] op_sel_hi:[1,0,1] neg_lo:[0,1,0] neg_hi:[0,1,0]
	v_pk_fma_f32 v[24:25], v[84:85], v[30:31], v[24:25] op_sel_hi:[1,0,1] neg_lo:[0,1,0] neg_hi:[0,1,0]
	v_pk_fma_f32 v[26:27], v[86:87], v[30:31], v[26:27] op_sel_hi:[1,0,1] neg_lo:[0,1,0] neg_hi:[0,1,0]
	ds_write_b32 v102, v39 offset:1280
	ds_read_b128 v[140:143], v195 offset:3072
	ds_read_b128 v[152:155], v195 offset:11264
	ds_read_b128 v[176:179], v195 offset:19456
	ds_read_b128 v[84:87], v195 offset:35840
	ds_read_b64 v[4:5], v196 offset:6144
	ds_read_b64 v[6:7], v36 offset:6144
	s_waitcnt lgkmcnt(7)
	v_pk_mul_f32 v[46:47], v[24:25], v[144:145] op_sel_hi:[0,1]
	v_pk_mul_f32 v[34:35], v[20:21], v[144:145] op_sel_hi:[0,1]
	v_pk_fma_f32 v[46:47], v[24:25], v[146:147], v[46:47] op_sel:[1,0,0] op_sel_hi:[1,1,1]
	v_pk_fma_f32 v[34:35], v[20:21], v[146:147], v[34:35] op_sel:[1,0,0] op_sel_hi:[1,1,1]
	v_pk_fma_f32 v[46:47], v[26:27], v[156:157], v[46:47] op_sel_hi:[0,1,1]
	v_pk_fma_f32 v[34:35], v[22:23], v[156:157], v[34:35] op_sel_hi:[0,1,1]
	v_pk_fma_f32 v[46:47], v[26:27], v[158:159], v[46:47] op_sel:[1,0,0] op_sel_hi:[1,1,1]
	v_pk_fma_f32 v[34:35], v[22:23], v[158:159], v[34:35] op_sel:[1,0,0] op_sel_hi:[1,1,1]
	v_pk_mul_f32 v[20:21], v[20:21], v[168:169]
	v_add_f32_dpp v28, v46, v34 row_half_mirror row_mask:0xf bank_mask:0xf
	v_add_f32_dpp v32, v47, v35 row_half_mirror row_mask:0xf bank_mask:0xf
	v_pk_mul_f32 v[22:23], v[22:23], v[170:171]
	v_add_f32_dpp v28, v28, v28 row_ror:8 row_mask:0xf bank_mask:0xf
	v_add_f32_dpp v32, v32, v32 row_ror:8 row_mask:0xf bank_mask:0xf
	v_pk_mul_f32 v[24:25], v[24:25], v[168:169]
	v_add_f32_dpp v28, v28, v28 quad_perm:[1,0,3,2] row_mask:0xf bank_mask:0xf
	v_add_f32_dpp v32, v32, v32 quad_perm:[1,0,3,2] row_mask:0xf bank_mask:0xf
	v_pk_mul_f32 v[26:27], v[26:27], v[170:171]
	v_add_f32_dpp v28, v28, v28 quad_perm:[2,3,0,1] row_mask:0xf bank_mask:0xf
	v_add_f32_dpp v32, v32, v32 quad_perm:[2,3,0,1] row_mask:0xf bank_mask:0xf
	v_pk_fma_f32 v[20:21], v[180:181], v[8:9], v[20:21] op_sel_hi:[1,0,1]
	v_mov_b32_dpp v30, v28 row_half_mirror row_mask:0xf bank_mask:0xf
	v_pk_fma_f32 v[22:23], v[182:183], v[8:9], v[22:23] op_sel_hi:[1,0,1]
	v_pk_fma_f32 v[24:25], v[180:181], v[10:11], v[24:25] op_sel_hi:[1,0,1]
	v_pk_fma_f32 v[26:27], v[182:183], v[10:11], v[26:27] op_sel_hi:[1,0,1]
	v_pk_fma_f32 v[20:21], v[88:89], v[28:29], v[20:21] op_sel_hi:[1,0,1] neg_lo:[0,1,0] neg_hi:[0,1,0]
	v_pk_fma_f32 v[22:23], v[90:91], v[28:29], v[22:23] op_sel_hi:[1,0,1] neg_lo:[0,1,0] neg_hi:[0,1,0]
	v_pk_fma_f32 v[24:25], v[88:89], v[30:31], v[24:25] op_sel_hi:[1,0,1] neg_lo:[0,1,0] neg_hi:[0,1,0]
	v_pk_fma_f32 v[26:27], v[90:91], v[30:31], v[26:27] op_sel_hi:[1,0,1] neg_lo:[0,1,0] neg_hi:[0,1,0]
	v_add_f32_e32 v39, v32, v9
	ds_write_b32 v102, v39 offset:1408
	ds_read_b128 v[144:147], v195 offset:3328
	ds_read_b128 v[156:159], v195 offset:11520
	ds_read_b128 v[180:183], v195 offset:19712
	ds_read_b128 v[88:91], v195 offset:36096
	ds_read_b64 v[8:9], v196 offset:6656
	ds_read_b64 v[10:11], v36 offset:6656
	s_waitcnt lgkmcnt(7)
	v_pk_mul_f32 v[46:47], v[24:25], v[140:141] op_sel_hi:[0,1]
	v_pk_mul_f32 v[34:35], v[20:21], v[140:141] op_sel_hi:[0,1]
	v_pk_fma_f32 v[46:47], v[24:25], v[142:143], v[46:47] op_sel:[1,0,0] op_sel_hi:[1,1,1]
	v_pk_fma_f32 v[34:35], v[20:21], v[142:143], v[34:35] op_sel:[1,0,0] op_sel_hi:[1,1,1]
	v_pk_fma_f32 v[46:47], v[26:27], v[152:153], v[46:47] op_sel_hi:[0,1,1]
	v_pk_fma_f32 v[34:35], v[22:23], v[152:153], v[34:35] op_sel_hi:[0,1,1]
	v_pk_fma_f32 v[46:47], v[26:27], v[154:155], v[46:47] op_sel:[1,0,0] op_sel_hi:[1,1,1]
	v_pk_fma_f32 v[34:35], v[22:23], v[154:155], v[34:35] op_sel:[1,0,0] op_sel_hi:[1,1,1]
	v_pk_fma_f32 v[20:21], v[176:177], v[4:5], v[20:21] op_sel_hi:[1,0,1]
	v_add_f32_dpp v28, v46, v34 row_half_mirror row_mask:0xf bank_mask:0xf
	v_add_f32_dpp v32, v47, v35 row_half_mirror row_mask:0xf bank_mask:0xf
	v_pk_fma_f32 v[22:23], v[178:179], v[4:5], v[22:23] op_sel_hi:[1,0,1]
	v_add_f32_dpp v28, v28, v28 row_ror:8 row_mask:0xf bank_mask:0xf
	v_add_f32_dpp v32, v32, v32 row_ror:8 row_mask:0xf bank_mask:0xf
	v_pk_fma_f32 v[24:25], v[176:177], v[6:7], v[24:25] op_sel_hi:[1,0,1]
	v_add_f32_dpp v28, v28, v28 quad_perm:[1,0,3,2] row_mask:0xf bank_mask:0xf
	v_add_f32_dpp v32, v32, v32 quad_perm:[1,0,3,2] row_mask:0xf bank_mask:0xf
	v_pk_fma_f32 v[26:27], v[178:179], v[6:7], v[26:27] op_sel_hi:[1,0,1]
	v_add_f32_dpp v28, v28, v28 quad_perm:[2,3,0,1] row_mask:0xf bank_mask:0xf
	v_add_f32_dpp v32, v32, v32 quad_perm:[2,3,0,1] row_mask:0xf bank_mask:0xf
	v_add_f32_e32 v39, v32, v5
	v_mov_b32_dpp v30, v28 row_half_mirror row_mask:0xf bank_mask:0xf
	v_pk_fma_f32 v[20:21], v[84:85], v[28:29], v[20:21] op_sel_hi:[1,0,1] neg_lo:[0,1,0] neg_hi:[0,1,0]
	v_pk_fma_f32 v[22:23], v[86:87], v[28:29], v[22:23] op_sel_hi:[1,0,1] neg_lo:[0,1,0] neg_hi:[0,1,0]
	v_pk_fma_f32 v[24:25], v[84:85], v[30:31], v[24:25] op_sel_hi:[1,0,1] neg_lo:[0,1,0] neg_hi:[0,1,0]
	v_pk_fma_f32 v[26:27], v[86:87], v[30:31], v[26:27] op_sel_hi:[1,0,1] neg_lo:[0,1,0] neg_hi:[0,1,0]
	ds_write_b32 v102, v39 offset:1536
	ds_read_b128 v[140:143], v195 offset:3584
	ds_read_b128 v[152:155], v195 offset:11776
	ds_read_b128 v[176:179], v195 offset:19968
	ds_read_b128 v[84:87], v195 offset:36352
	ds_read_b64 v[4:5], v196 offset:7168
	ds_read_b64 v[6:7], v36 offset:7168
	s_waitcnt lgkmcnt(7)
	v_pk_mul_f32 v[46:47], v[24:25], v[144:145] op_sel_hi:[0,1]
	v_pk_mul_f32 v[34:35], v[20:21], v[144:145] op_sel_hi:[0,1]
	v_pk_fma_f32 v[46:47], v[24:25], v[146:147], v[46:47] op_sel:[1,0,0] op_sel_hi:[1,1,1]
	v_pk_fma_f32 v[34:35], v[20:21], v[146:147], v[34:35] op_sel:[1,0,0] op_sel_hi:[1,1,1]
	v_pk_fma_f32 v[46:47], v[26:27], v[156:157], v[46:47] op_sel_hi:[0,1,1]
	v_pk_fma_f32 v[34:35], v[22:23], v[156:157], v[34:35] op_sel_hi:[0,1,1]
	v_pk_fma_f32 v[46:47], v[26:27], v[158:159], v[46:47] op_sel:[1,0,0] op_sel_hi:[1,1,1]
	v_pk_fma_f32 v[34:35], v[22:23], v[158:159], v[34:35] op_sel:[1,0,0] op_sel_hi:[1,1,1]
	v_pk_fma_f32 v[20:21], v[180:181], v[8:9], v[20:21] op_sel_hi:[1,0,1]
	v_add_f32_dpp v28, v46, v34 row_half_mirror row_mask:0xf bank_mask:0xf
	v_add_f32_dpp v32, v47, v35 row_half_mirror row_mask:0xf bank_mask:0xf
	v_pk_fma_f32 v[22:23], v[182:183], v[8:9], v[22:23] op_sel_hi:[1,0,1]
	v_add_f32_dpp v28, v28, v28 row_ror:8 row_mask:0xf bank_mask:0xf
	v_add_f32_dpp v32, v32, v32 row_ror:8 row_mask:0xf bank_mask:0xf
	v_pk_fma_f32 v[24:25], v[180:181], v[10:11], v[24:25] op_sel_hi:[1,0,1]
	v_add_f32_dpp v28, v28, v28 quad_perm:[1,0,3,2] row_mask:0xf bank_mask:0xf
	v_add_f32_dpp v32, v32, v32 quad_perm:[1,0,3,2] row_mask:0xf bank_mask:0xf
	v_pk_fma_f32 v[26:27], v[182:183], v[10:11], v[26:27] op_sel_hi:[1,0,1]
	v_add_f32_dpp v28, v28, v28 quad_perm:[2,3,0,1] row_mask:0xf bank_mask:0xf
	v_add_f32_dpp v32, v32, v32 quad_perm:[2,3,0,1] row_mask:0xf bank_mask:0xf
	v_add_f32_e32 v39, v32, v9
	v_mov_b32_dpp v30, v28 row_half_mirror row_mask:0xf bank_mask:0xf
	v_pk_fma_f32 v[20:21], v[88:89], v[28:29], v[20:21] op_sel_hi:[1,0,1] neg_lo:[0,1,0] neg_hi:[0,1,0]
	v_pk_fma_f32 v[22:23], v[90:91], v[28:29], v[22:23] op_sel_hi:[1,0,1] neg_lo:[0,1,0] neg_hi:[0,1,0]
	v_pk_fma_f32 v[24:25], v[88:89], v[30:31], v[24:25] op_sel_hi:[1,0,1] neg_lo:[0,1,0] neg_hi:[0,1,0]
	v_pk_fma_f32 v[26:27], v[90:91], v[30:31], v[26:27] op_sel_hi:[1,0,1] neg_lo:[0,1,0] neg_hi:[0,1,0]
	ds_write_b32 v102, v39 offset:1664
	ds_read_b128 v[144:147], v195 offset:3840
	ds_read_b128 v[156:159], v195 offset:12032
	ds_read_b128 v[168:171], v195 offset:28416
	ds_read_b128 v[180:183], v195 offset:20224
	ds_read_b128 v[88:91], v195 offset:36608
	ds_read_b64 v[8:9], v196 offset:7680
	ds_read_b64 v[10:11], v36 offset:7680
	s_waitcnt lgkmcnt(8)
	v_pk_mul_f32 v[46:47], v[24:25], v[140:141] op_sel_hi:[0,1]
	v_pk_mul_f32 v[34:35], v[20:21], v[140:141] op_sel_hi:[0,1]
	v_pk_fma_f32 v[46:47], v[24:25], v[142:143], v[46:47] op_sel:[1,0,0] op_sel_hi:[1,1,1]
	v_pk_fma_f32 v[34:35], v[20:21], v[142:143], v[34:35] op_sel:[1,0,0] op_sel_hi:[1,1,1]
	v_pk_fma_f32 v[46:47], v[26:27], v[152:153], v[46:47] op_sel_hi:[0,1,1]
	v_pk_fma_f32 v[34:35], v[22:23], v[152:153], v[34:35] op_sel_hi:[0,1,1]
	v_pk_fma_f32 v[46:47], v[26:27], v[154:155], v[46:47] op_sel:[1,0,0] op_sel_hi:[1,1,1]
	v_pk_fma_f32 v[34:35], v[22:23], v[154:155], v[34:35] op_sel:[1,0,0] op_sel_hi:[1,1,1]
	v_pk_fma_f32 v[20:21], v[176:177], v[4:5], v[20:21] op_sel_hi:[1,0,1]
	v_add_f32_dpp v28, v46, v34 row_half_mirror row_mask:0xf bank_mask:0xf
	v_add_f32_dpp v32, v47, v35 row_half_mirror row_mask:0xf bank_mask:0xf
	v_pk_fma_f32 v[22:23], v[178:179], v[4:5], v[22:23] op_sel_hi:[1,0,1]
	v_add_f32_dpp v28, v28, v28 row_ror:8 row_mask:0xf bank_mask:0xf
	v_add_f32_dpp v32, v32, v32 row_ror:8 row_mask:0xf bank_mask:0xf
	v_pk_fma_f32 v[24:25], v[176:177], v[6:7], v[24:25] op_sel_hi:[1,0,1]
	v_add_f32_dpp v28, v28, v28 quad_perm:[1,0,3,2] row_mask:0xf bank_mask:0xf
	v_add_f32_dpp v32, v32, v32 quad_perm:[1,0,3,2] row_mask:0xf bank_mask:0xf
	v_pk_fma_f32 v[26:27], v[178:179], v[6:7], v[26:27] op_sel_hi:[1,0,1]
	v_add_f32_dpp v28, v28, v28 quad_perm:[2,3,0,1] row_mask:0xf bank_mask:0xf
	v_add_f32_dpp v32, v32, v32 quad_perm:[2,3,0,1] row_mask:0xf bank_mask:0xf
	v_add_f32_e32 v39, v32, v5
	v_mov_b32_dpp v30, v28 row_half_mirror row_mask:0xf bank_mask:0xf
	v_pk_fma_f32 v[20:21], v[84:85], v[28:29], v[20:21] op_sel_hi:[1,0,1] neg_lo:[0,1,0] neg_hi:[0,1,0]
	v_pk_fma_f32 v[22:23], v[86:87], v[28:29], v[22:23] op_sel_hi:[1,0,1] neg_lo:[0,1,0] neg_hi:[0,1,0]
	v_pk_fma_f32 v[24:25], v[84:85], v[30:31], v[24:25] op_sel_hi:[1,0,1] neg_lo:[0,1,0] neg_hi:[0,1,0]
	v_pk_fma_f32 v[26:27], v[86:87], v[30:31], v[26:27] op_sel_hi:[1,0,1] neg_lo:[0,1,0] neg_hi:[0,1,0]
	ds_write_b32 v102, v39 offset:1792
	ds_read_b128 v[140:143], v195 offset:4096
	ds_read_b128 v[152:155], v195 offset:12288
	ds_read_b128 v[176:179], v195 offset:20480
	ds_read_b128 v[84:87], v195 offset:36864
	ds_read_b64 v[4:5], v196 offset:8192
	ds_read_b64 v[6:7], v36 offset:8192
	s_waitcnt lgkmcnt(7)
	v_pk_mul_f32 v[46:47], v[24:25], v[144:145] op_sel_hi:[0,1]
	v_pk_mul_f32 v[34:35], v[20:21], v[144:145] op_sel_hi:[0,1]
	v_pk_fma_f32 v[46:47], v[24:25], v[146:147], v[46:47] op_sel:[1,0,0] op_sel_hi:[1,1,1]
	v_pk_fma_f32 v[34:35], v[20:21], v[146:147], v[34:35] op_sel:[1,0,0] op_sel_hi:[1,1,1]
	v_pk_fma_f32 v[46:47], v[26:27], v[156:157], v[46:47] op_sel_hi:[0,1,1]
	v_pk_fma_f32 v[34:35], v[22:23], v[156:157], v[34:35] op_sel_hi:[0,1,1]
	v_pk_fma_f32 v[46:47], v[26:27], v[158:159], v[46:47] op_sel:[1,0,0] op_sel_hi:[1,1,1]
	v_pk_fma_f32 v[34:35], v[22:23], v[158:159], v[34:35] op_sel:[1,0,0] op_sel_hi:[1,1,1]
	v_pk_mul_f32 v[20:21], v[20:21], v[168:169]
	v_add_f32_dpp v28, v46, v34 row_half_mirror row_mask:0xf bank_mask:0xf
	v_add_f32_dpp v32, v47, v35 row_half_mirror row_mask:0xf bank_mask:0xf
	v_pk_mul_f32 v[22:23], v[22:23], v[170:171]
	v_add_f32_dpp v28, v28, v28 row_ror:8 row_mask:0xf bank_mask:0xf
	v_add_f32_dpp v32, v32, v32 row_ror:8 row_mask:0xf bank_mask:0xf
	v_pk_mul_f32 v[24:25], v[24:25], v[168:169]
	v_add_f32_dpp v28, v28, v28 quad_perm:[1,0,3,2] row_mask:0xf bank_mask:0xf
	v_add_f32_dpp v32, v32, v32 quad_perm:[1,0,3,2] row_mask:0xf bank_mask:0xf
	v_pk_mul_f32 v[26:27], v[26:27], v[170:171]
	v_add_f32_dpp v28, v28, v28 quad_perm:[2,3,0,1] row_mask:0xf bank_mask:0xf
	v_add_f32_dpp v32, v32, v32 quad_perm:[2,3,0,1] row_mask:0xf bank_mask:0xf
	v_pk_fma_f32 v[20:21], v[180:181], v[8:9], v[20:21] op_sel_hi:[1,0,1]
	v_mov_b32_dpp v30, v28 row_half_mirror row_mask:0xf bank_mask:0xf
	v_pk_fma_f32 v[22:23], v[182:183], v[8:9], v[22:23] op_sel_hi:[1,0,1]
	v_pk_fma_f32 v[24:25], v[180:181], v[10:11], v[24:25] op_sel_hi:[1,0,1]
	v_pk_fma_f32 v[26:27], v[182:183], v[10:11], v[26:27] op_sel_hi:[1,0,1]
	v_pk_fma_f32 v[20:21], v[88:89], v[28:29], v[20:21] op_sel_hi:[1,0,1] neg_lo:[0,1,0] neg_hi:[0,1,0]
	v_pk_fma_f32 v[22:23], v[90:91], v[28:29], v[22:23] op_sel_hi:[1,0,1] neg_lo:[0,1,0] neg_hi:[0,1,0]
	v_pk_fma_f32 v[24:25], v[88:89], v[30:31], v[24:25] op_sel_hi:[1,0,1] neg_lo:[0,1,0] neg_hi:[0,1,0]
	v_pk_fma_f32 v[26:27], v[90:91], v[30:31], v[26:27] op_sel_hi:[1,0,1] neg_lo:[0,1,0] neg_hi:[0,1,0]
	v_add_f32_e32 v39, v32, v9
	ds_write_b32 v102, v39 offset:1920
	ds_read_b128 v[144:147], v195 offset:4352
	ds_read_b128 v[156:159], v195 offset:12544
	ds_read_b128 v[180:183], v195 offset:20736
	ds_read_b128 v[88:91], v195 offset:37120
	ds_read_b64 v[8:9], v196 offset:8704
	ds_read_b64 v[10:11], v36 offset:8704
	s_waitcnt lgkmcnt(7)
	v_pk_mul_f32 v[46:47], v[24:25], v[140:141] op_sel_hi:[0,1]
	v_pk_mul_f32 v[34:35], v[20:21], v[140:141] op_sel_hi:[0,1]
	v_pk_fma_f32 v[46:47], v[24:25], v[142:143], v[46:47] op_sel:[1,0,0] op_sel_hi:[1,1,1]
	v_pk_fma_f32 v[34:35], v[20:21], v[142:143], v[34:35] op_sel:[1,0,0] op_sel_hi:[1,1,1]
	v_pk_fma_f32 v[46:47], v[26:27], v[152:153], v[46:47] op_sel_hi:[0,1,1]
	v_pk_fma_f32 v[34:35], v[22:23], v[152:153], v[34:35] op_sel_hi:[0,1,1]
	v_pk_fma_f32 v[46:47], v[26:27], v[154:155], v[46:47] op_sel:[1,0,0] op_sel_hi:[1,1,1]
	v_pk_fma_f32 v[34:35], v[22:23], v[154:155], v[34:35] op_sel:[1,0,0] op_sel_hi:[1,1,1]
	v_pk_fma_f32 v[20:21], v[176:177], v[4:5], v[20:21] op_sel_hi:[1,0,1]
	v_add_f32_dpp v28, v46, v34 row_half_mirror row_mask:0xf bank_mask:0xf
	v_add_f32_dpp v32, v47, v35 row_half_mirror row_mask:0xf bank_mask:0xf
	v_pk_fma_f32 v[22:23], v[178:179], v[4:5], v[22:23] op_sel_hi:[1,0,1]
	v_add_f32_dpp v28, v28, v28 row_ror:8 row_mask:0xf bank_mask:0xf
	v_add_f32_dpp v32, v32, v32 row_ror:8 row_mask:0xf bank_mask:0xf
	v_pk_fma_f32 v[24:25], v[176:177], v[6:7], v[24:25] op_sel_hi:[1,0,1]
	v_add_f32_dpp v28, v28, v28 quad_perm:[1,0,3,2] row_mask:0xf bank_mask:0xf
	v_add_f32_dpp v32, v32, v32 quad_perm:[1,0,3,2] row_mask:0xf bank_mask:0xf
	v_pk_fma_f32 v[26:27], v[178:179], v[6:7], v[26:27] op_sel_hi:[1,0,1]
	v_add_f32_dpp v28, v28, v28 quad_perm:[2,3,0,1] row_mask:0xf bank_mask:0xf
	v_add_f32_dpp v32, v32, v32 quad_perm:[2,3,0,1] row_mask:0xf bank_mask:0xf
	v_add_f32_e32 v39, v32, v5
	v_mov_b32_dpp v30, v28 row_half_mirror row_mask:0xf bank_mask:0xf
	v_pk_fma_f32 v[20:21], v[84:85], v[28:29], v[20:21] op_sel_hi:[1,0,1] neg_lo:[0,1,0] neg_hi:[0,1,0]
	v_pk_fma_f32 v[22:23], v[86:87], v[28:29], v[22:23] op_sel_hi:[1,0,1] neg_lo:[0,1,0] neg_hi:[0,1,0]
	v_pk_fma_f32 v[24:25], v[84:85], v[30:31], v[24:25] op_sel_hi:[1,0,1] neg_lo:[0,1,0] neg_hi:[0,1,0]
	v_pk_fma_f32 v[26:27], v[86:87], v[30:31], v[26:27] op_sel_hi:[1,0,1] neg_lo:[0,1,0] neg_hi:[0,1,0]
	ds_write_b32 v102, v39 offset:2048
	ds_read_b128 v[140:143], v195 offset:4608
	ds_read_b128 v[152:155], v195 offset:12800
	ds_read_b128 v[176:179], v195 offset:20992
	ds_read_b128 v[84:87], v195 offset:37376
	ds_read_b64 v[4:5], v196 offset:9216
	ds_read_b64 v[6:7], v36 offset:9216
	s_waitcnt lgkmcnt(7)
	v_pk_mul_f32 v[46:47], v[24:25], v[144:145] op_sel_hi:[0,1]
	v_pk_mul_f32 v[34:35], v[20:21], v[144:145] op_sel_hi:[0,1]
	v_pk_fma_f32 v[46:47], v[24:25], v[146:147], v[46:47] op_sel:[1,0,0] op_sel_hi:[1,1,1]
	v_pk_fma_f32 v[34:35], v[20:21], v[146:147], v[34:35] op_sel:[1,0,0] op_sel_hi:[1,1,1]
	v_pk_fma_f32 v[46:47], v[26:27], v[156:157], v[46:47] op_sel_hi:[0,1,1]
	v_pk_fma_f32 v[34:35], v[22:23], v[156:157], v[34:35] op_sel_hi:[0,1,1]
	v_pk_fma_f32 v[46:47], v[26:27], v[158:159], v[46:47] op_sel:[1,0,0] op_sel_hi:[1,1,1]
	v_pk_fma_f32 v[34:35], v[22:23], v[158:159], v[34:35] op_sel:[1,0,0] op_sel_hi:[1,1,1]
	v_pk_fma_f32 v[20:21], v[180:181], v[8:9], v[20:21] op_sel_hi:[1,0,1]
	v_add_f32_dpp v28, v46, v34 row_half_mirror row_mask:0xf bank_mask:0xf
	v_add_f32_dpp v32, v47, v35 row_half_mirror row_mask:0xf bank_mask:0xf
	v_pk_fma_f32 v[22:23], v[182:183], v[8:9], v[22:23] op_sel_hi:[1,0,1]
	v_add_f32_dpp v28, v28, v28 row_ror:8 row_mask:0xf bank_mask:0xf
	v_add_f32_dpp v32, v32, v32 row_ror:8 row_mask:0xf bank_mask:0xf
	v_pk_fma_f32 v[24:25], v[180:181], v[10:11], v[24:25] op_sel_hi:[1,0,1]
	v_add_f32_dpp v28, v28, v28 quad_perm:[1,0,3,2] row_mask:0xf bank_mask:0xf
	v_add_f32_dpp v32, v32, v32 quad_perm:[1,0,3,2] row_mask:0xf bank_mask:0xf
	v_pk_fma_f32 v[26:27], v[182:183], v[10:11], v[26:27] op_sel_hi:[1,0,1]
	v_add_f32_dpp v28, v28, v28 quad_perm:[2,3,0,1] row_mask:0xf bank_mask:0xf
	v_add_f32_dpp v32, v32, v32 quad_perm:[2,3,0,1] row_mask:0xf bank_mask:0xf
	v_add_f32_e32 v39, v32, v9
	v_mov_b32_dpp v30, v28 row_half_mirror row_mask:0xf bank_mask:0xf
	v_pk_fma_f32 v[20:21], v[88:89], v[28:29], v[20:21] op_sel_hi:[1,0,1] neg_lo:[0,1,0] neg_hi:[0,1,0]
	v_pk_fma_f32 v[22:23], v[90:91], v[28:29], v[22:23] op_sel_hi:[1,0,1] neg_lo:[0,1,0] neg_hi:[0,1,0]
	v_pk_fma_f32 v[24:25], v[88:89], v[30:31], v[24:25] op_sel_hi:[1,0,1] neg_lo:[0,1,0] neg_hi:[0,1,0]
	v_pk_fma_f32 v[26:27], v[90:91], v[30:31], v[26:27] op_sel_hi:[1,0,1] neg_lo:[0,1,0] neg_hi:[0,1,0]
	ds_write_b32 v102, v39 offset:2176
	ds_read_b128 v[144:147], v195 offset:4864
	ds_read_b128 v[156:159], v195 offset:13056
	ds_read_b128 v[168:171], v195 offset:29440
	ds_read_b128 v[180:183], v195 offset:21248
	ds_read_b128 v[88:91], v195 offset:37632
	ds_read_b64 v[8:9], v196 offset:9728
	ds_read_b64 v[10:11], v36 offset:9728
	s_waitcnt lgkmcnt(8)
	v_pk_mul_f32 v[46:47], v[24:25], v[140:141] op_sel_hi:[0,1]
	v_pk_mul_f32 v[34:35], v[20:21], v[140:141] op_sel_hi:[0,1]
	v_pk_fma_f32 v[46:47], v[24:25], v[142:143], v[46:47] op_sel:[1,0,0] op_sel_hi:[1,1,1]
	v_pk_fma_f32 v[34:35], v[20:21], v[142:143], v[34:35] op_sel:[1,0,0] op_sel_hi:[1,1,1]
	v_pk_fma_f32 v[46:47], v[26:27], v[152:153], v[46:47] op_sel_hi:[0,1,1]
	v_pk_fma_f32 v[34:35], v[22:23], v[152:153], v[34:35] op_sel_hi:[0,1,1]
	v_pk_fma_f32 v[46:47], v[26:27], v[154:155], v[46:47] op_sel:[1,0,0] op_sel_hi:[1,1,1]
	v_pk_fma_f32 v[34:35], v[22:23], v[154:155], v[34:35] op_sel:[1,0,0] op_sel_hi:[1,1,1]
	v_pk_fma_f32 v[20:21], v[176:177], v[4:5], v[20:21] op_sel_hi:[1,0,1]
	v_add_f32_dpp v28, v46, v34 row_half_mirror row_mask:0xf bank_mask:0xf
	v_add_f32_dpp v32, v47, v35 row_half_mirror row_mask:0xf bank_mask:0xf
	v_pk_fma_f32 v[22:23], v[178:179], v[4:5], v[22:23] op_sel_hi:[1,0,1]
	v_add_f32_dpp v28, v28, v28 row_ror:8 row_mask:0xf bank_mask:0xf
	v_add_f32_dpp v32, v32, v32 row_ror:8 row_mask:0xf bank_mask:0xf
	v_pk_fma_f32 v[24:25], v[176:177], v[6:7], v[24:25] op_sel_hi:[1,0,1]
	v_add_f32_dpp v28, v28, v28 quad_perm:[1,0,3,2] row_mask:0xf bank_mask:0xf
	v_add_f32_dpp v32, v32, v32 quad_perm:[1,0,3,2] row_mask:0xf bank_mask:0xf
	v_pk_fma_f32 v[26:27], v[178:179], v[6:7], v[26:27] op_sel_hi:[1,0,1]
	v_add_f32_dpp v28, v28, v28 quad_perm:[2,3,0,1] row_mask:0xf bank_mask:0xf
	v_add_f32_dpp v32, v32, v32 quad_perm:[2,3,0,1] row_mask:0xf bank_mask:0xf
	v_add_f32_e32 v39, v32, v5
	v_mov_b32_dpp v30, v28 row_half_mirror row_mask:0xf bank_mask:0xf
	v_pk_fma_f32 v[20:21], v[84:85], v[28:29], v[20:21] op_sel_hi:[1,0,1] neg_lo:[0,1,0] neg_hi:[0,1,0]
	v_pk_fma_f32 v[22:23], v[86:87], v[28:29], v[22:23] op_sel_hi:[1,0,1] neg_lo:[0,1,0] neg_hi:[0,1,0]
	v_pk_fma_f32 v[24:25], v[84:85], v[30:31], v[24:25] op_sel_hi:[1,0,1] neg_lo:[0,1,0] neg_hi:[0,1,0]
	v_pk_fma_f32 v[26:27], v[86:87], v[30:31], v[26:27] op_sel_hi:[1,0,1] neg_lo:[0,1,0] neg_hi:[0,1,0]
	ds_write_b32 v102, v39 offset:2304
	ds_read_b128 v[140:143], v195 offset:5120
	ds_read_b128 v[152:155], v195 offset:13312
	ds_read_b128 v[176:179], v195 offset:21504
	ds_read_b128 v[84:87], v195 offset:37888
	ds_read_b64 v[4:5], v196 offset:10240
	ds_read_b64 v[6:7], v36 offset:10240
	s_waitcnt lgkmcnt(7)
	v_pk_mul_f32 v[46:47], v[24:25], v[144:145] op_sel_hi:[0,1]
	v_pk_mul_f32 v[34:35], v[20:21], v[144:145] op_sel_hi:[0,1]
	v_pk_fma_f32 v[46:47], v[24:25], v[146:147], v[46:47] op_sel:[1,0,0] op_sel_hi:[1,1,1]
	v_pk_fma_f32 v[34:35], v[20:21], v[146:147], v[34:35] op_sel:[1,0,0] op_sel_hi:[1,1,1]
	v_pk_fma_f32 v[46:47], v[26:27], v[156:157], v[46:47] op_sel_hi:[0,1,1]
	v_pk_fma_f32 v[34:35], v[22:23], v[156:157], v[34:35] op_sel_hi:[0,1,1]
	v_pk_fma_f32 v[46:47], v[26:27], v[158:159], v[46:47] op_sel:[1,0,0] op_sel_hi:[1,1,1]
	v_pk_fma_f32 v[34:35], v[22:23], v[158:159], v[34:35] op_sel:[1,0,0] op_sel_hi:[1,1,1]
	v_pk_mul_f32 v[20:21], v[20:21], v[168:169]
	v_add_f32_dpp v28, v46, v34 row_half_mirror row_mask:0xf bank_mask:0xf
	v_add_f32_dpp v32, v47, v35 row_half_mirror row_mask:0xf bank_mask:0xf
	v_pk_mul_f32 v[22:23], v[22:23], v[170:171]
	v_add_f32_dpp v28, v28, v28 row_ror:8 row_mask:0xf bank_mask:0xf
	v_add_f32_dpp v32, v32, v32 row_ror:8 row_mask:0xf bank_mask:0xf
	v_pk_mul_f32 v[24:25], v[24:25], v[168:169]
	v_add_f32_dpp v28, v28, v28 quad_perm:[1,0,3,2] row_mask:0xf bank_mask:0xf
	v_add_f32_dpp v32, v32, v32 quad_perm:[1,0,3,2] row_mask:0xf bank_mask:0xf
	v_pk_mul_f32 v[26:27], v[26:27], v[170:171]
	v_add_f32_dpp v28, v28, v28 quad_perm:[2,3,0,1] row_mask:0xf bank_mask:0xf
	v_add_f32_dpp v32, v32, v32 quad_perm:[2,3,0,1] row_mask:0xf bank_mask:0xf
	v_pk_fma_f32 v[20:21], v[180:181], v[8:9], v[20:21] op_sel_hi:[1,0,1]
	v_mov_b32_dpp v30, v28 row_half_mirror row_mask:0xf bank_mask:0xf
	v_pk_fma_f32 v[22:23], v[182:183], v[8:9], v[22:23] op_sel_hi:[1,0,1]
	v_pk_fma_f32 v[24:25], v[180:181], v[10:11], v[24:25] op_sel_hi:[1,0,1]
	v_pk_fma_f32 v[26:27], v[182:183], v[10:11], v[26:27] op_sel_hi:[1,0,1]
	v_pk_fma_f32 v[20:21], v[88:89], v[28:29], v[20:21] op_sel_hi:[1,0,1] neg_lo:[0,1,0] neg_hi:[0,1,0]
	v_pk_fma_f32 v[22:23], v[90:91], v[28:29], v[22:23] op_sel_hi:[1,0,1] neg_lo:[0,1,0] neg_hi:[0,1,0]
	v_pk_fma_f32 v[24:25], v[88:89], v[30:31], v[24:25] op_sel_hi:[1,0,1] neg_lo:[0,1,0] neg_hi:[0,1,0]
	v_pk_fma_f32 v[26:27], v[90:91], v[30:31], v[26:27] op_sel_hi:[1,0,1] neg_lo:[0,1,0] neg_hi:[0,1,0]
	v_add_f32_e32 v39, v32, v9
	ds_write_b32 v102, v39 offset:2432
	ds_read_b128 v[144:147], v195 offset:5376
	ds_read_b128 v[156:159], v195 offset:13568
	ds_read_b128 v[180:183], v195 offset:21760
	ds_read_b128 v[88:91], v195 offset:38144
	ds_read_b64 v[8:9], v196 offset:10752
	ds_read_b64 v[10:11], v36 offset:10752
	s_waitcnt lgkmcnt(7)
	v_pk_mul_f32 v[46:47], v[24:25], v[140:141] op_sel_hi:[0,1]
	v_pk_mul_f32 v[34:35], v[20:21], v[140:141] op_sel_hi:[0,1]
	v_pk_fma_f32 v[46:47], v[24:25], v[142:143], v[46:47] op_sel:[1,0,0] op_sel_hi:[1,1,1]
	v_pk_fma_f32 v[34:35], v[20:21], v[142:143], v[34:35] op_sel:[1,0,0] op_sel_hi:[1,1,1]
	v_pk_fma_f32 v[46:47], v[26:27], v[152:153], v[46:47] op_sel_hi:[0,1,1]
	v_pk_fma_f32 v[34:35], v[22:23], v[152:153], v[34:35] op_sel_hi:[0,1,1]
	v_pk_fma_f32 v[46:47], v[26:27], v[154:155], v[46:47] op_sel:[1,0,0] op_sel_hi:[1,1,1]
	v_pk_fma_f32 v[34:35], v[22:23], v[154:155], v[34:35] op_sel:[1,0,0] op_sel_hi:[1,1,1]
	v_pk_fma_f32 v[20:21], v[176:177], v[4:5], v[20:21] op_sel_hi:[1,0,1]
	v_add_f32_dpp v28, v46, v34 row_half_mirror row_mask:0xf bank_mask:0xf
	v_add_f32_dpp v32, v47, v35 row_half_mirror row_mask:0xf bank_mask:0xf
	v_pk_fma_f32 v[22:23], v[178:179], v[4:5], v[22:23] op_sel_hi:[1,0,1]
	v_add_f32_dpp v28, v28, v28 row_ror:8 row_mask:0xf bank_mask:0xf
	v_add_f32_dpp v32, v32, v32 row_ror:8 row_mask:0xf bank_mask:0xf
	v_pk_fma_f32 v[24:25], v[176:177], v[6:7], v[24:25] op_sel_hi:[1,0,1]
	v_add_f32_dpp v28, v28, v28 quad_perm:[1,0,3,2] row_mask:0xf bank_mask:0xf
	v_add_f32_dpp v32, v32, v32 quad_perm:[1,0,3,2] row_mask:0xf bank_mask:0xf
	v_pk_fma_f32 v[26:27], v[178:179], v[6:7], v[26:27] op_sel_hi:[1,0,1]
	v_add_f32_dpp v28, v28, v28 quad_perm:[2,3,0,1] row_mask:0xf bank_mask:0xf
	v_add_f32_dpp v32, v32, v32 quad_perm:[2,3,0,1] row_mask:0xf bank_mask:0xf
	v_add_f32_e32 v39, v32, v5
	v_mov_b32_dpp v30, v28 row_half_mirror row_mask:0xf bank_mask:0xf
	v_pk_fma_f32 v[20:21], v[84:85], v[28:29], v[20:21] op_sel_hi:[1,0,1] neg_lo:[0,1,0] neg_hi:[0,1,0]
	v_pk_fma_f32 v[22:23], v[86:87], v[28:29], v[22:23] op_sel_hi:[1,0,1] neg_lo:[0,1,0] neg_hi:[0,1,0]
	v_pk_fma_f32 v[24:25], v[84:85], v[30:31], v[24:25] op_sel_hi:[1,0,1] neg_lo:[0,1,0] neg_hi:[0,1,0]
	v_pk_fma_f32 v[26:27], v[86:87], v[30:31], v[26:27] op_sel_hi:[1,0,1] neg_lo:[0,1,0] neg_hi:[0,1,0]
	ds_write_b32 v102, v39 offset:2560
	ds_read_b128 v[140:143], v195 offset:5632
	ds_read_b128 v[152:155], v195 offset:13824
	ds_read_b128 v[176:179], v195 offset:22016
	ds_read_b128 v[84:87], v195 offset:38400
	ds_read_b64 v[4:5], v196 offset:11264
	ds_read_b64 v[6:7], v36 offset:11264
	s_waitcnt lgkmcnt(7)
	v_pk_mul_f32 v[46:47], v[24:25], v[144:145] op_sel_hi:[0,1]
	v_pk_mul_f32 v[34:35], v[20:21], v[144:145] op_sel_hi:[0,1]
	v_pk_fma_f32 v[46:47], v[24:25], v[146:147], v[46:47] op_sel:[1,0,0] op_sel_hi:[1,1,1]
	v_pk_fma_f32 v[34:35], v[20:21], v[146:147], v[34:35] op_sel:[1,0,0] op_sel_hi:[1,1,1]
	v_pk_fma_f32 v[46:47], v[26:27], v[156:157], v[46:47] op_sel_hi:[0,1,1]
	v_pk_fma_f32 v[34:35], v[22:23], v[156:157], v[34:35] op_sel_hi:[0,1,1]
	v_pk_fma_f32 v[46:47], v[26:27], v[158:159], v[46:47] op_sel:[1,0,0] op_sel_hi:[1,1,1]
	v_pk_fma_f32 v[34:35], v[22:23], v[158:159], v[34:35] op_sel:[1,0,0] op_sel_hi:[1,1,1]
	v_pk_fma_f32 v[20:21], v[180:181], v[8:9], v[20:21] op_sel_hi:[1,0,1]
	v_add_f32_dpp v28, v46, v34 row_half_mirror row_mask:0xf bank_mask:0xf
	v_add_f32_dpp v32, v47, v35 row_half_mirror row_mask:0xf bank_mask:0xf
	v_pk_fma_f32 v[22:23], v[182:183], v[8:9], v[22:23] op_sel_hi:[1,0,1]
	v_add_f32_dpp v28, v28, v28 row_ror:8 row_mask:0xf bank_mask:0xf
	v_add_f32_dpp v32, v32, v32 row_ror:8 row_mask:0xf bank_mask:0xf
	v_pk_fma_f32 v[24:25], v[180:181], v[10:11], v[24:25] op_sel_hi:[1,0,1]
	v_add_f32_dpp v28, v28, v28 quad_perm:[1,0,3,2] row_mask:0xf bank_mask:0xf
	v_add_f32_dpp v32, v32, v32 quad_perm:[1,0,3,2] row_mask:0xf bank_mask:0xf
	v_pk_fma_f32 v[26:27], v[182:183], v[10:11], v[26:27] op_sel_hi:[1,0,1]
	v_add_f32_dpp v28, v28, v28 quad_perm:[2,3,0,1] row_mask:0xf bank_mask:0xf
	v_add_f32_dpp v32, v32, v32 quad_perm:[2,3,0,1] row_mask:0xf bank_mask:0xf
	v_add_f32_e32 v39, v32, v9
	v_mov_b32_dpp v30, v28 row_half_mirror row_mask:0xf bank_mask:0xf
	v_pk_fma_f32 v[20:21], v[88:89], v[28:29], v[20:21] op_sel_hi:[1,0,1] neg_lo:[0,1,0] neg_hi:[0,1,0]
	v_pk_fma_f32 v[22:23], v[90:91], v[28:29], v[22:23] op_sel_hi:[1,0,1] neg_lo:[0,1,0] neg_hi:[0,1,0]
	v_pk_fma_f32 v[24:25], v[88:89], v[30:31], v[24:25] op_sel_hi:[1,0,1] neg_lo:[0,1,0] neg_hi:[0,1,0]
	v_pk_fma_f32 v[26:27], v[90:91], v[30:31], v[26:27] op_sel_hi:[1,0,1] neg_lo:[0,1,0] neg_hi:[0,1,0]
	ds_write_b32 v102, v39 offset:2688
	ds_read_b128 v[144:147], v195 offset:5888
	ds_read_b128 v[156:159], v195 offset:14080
	ds_read_b128 v[168:171], v195 offset:30464
	ds_read_b128 v[180:183], v195 offset:22272
	ds_read_b128 v[88:91], v195 offset:38656
	ds_read_b64 v[8:9], v196 offset:11776
	ds_read_b64 v[10:11], v36 offset:11776
	s_waitcnt lgkmcnt(8)
	v_pk_mul_f32 v[46:47], v[24:25], v[140:141] op_sel_hi:[0,1]
	v_pk_mul_f32 v[34:35], v[20:21], v[140:141] op_sel_hi:[0,1]
	v_pk_fma_f32 v[46:47], v[24:25], v[142:143], v[46:47] op_sel:[1,0,0] op_sel_hi:[1,1,1]
	v_pk_fma_f32 v[34:35], v[20:21], v[142:143], v[34:35] op_sel:[1,0,0] op_sel_hi:[1,1,1]
	v_pk_fma_f32 v[46:47], v[26:27], v[152:153], v[46:47] op_sel_hi:[0,1,1]
	v_pk_fma_f32 v[34:35], v[22:23], v[152:153], v[34:35] op_sel_hi:[0,1,1]
	v_pk_fma_f32 v[46:47], v[26:27], v[154:155], v[46:47] op_sel:[1,0,0] op_sel_hi:[1,1,1]
	v_pk_fma_f32 v[34:35], v[22:23], v[154:155], v[34:35] op_sel:[1,0,0] op_sel_hi:[1,1,1]
	v_pk_fma_f32 v[20:21], v[176:177], v[4:5], v[20:21] op_sel_hi:[1,0,1]
	v_add_f32_dpp v28, v46, v34 row_half_mirror row_mask:0xf bank_mask:0xf
	v_add_f32_dpp v32, v47, v35 row_half_mirror row_mask:0xf bank_mask:0xf
	v_pk_fma_f32 v[22:23], v[178:179], v[4:5], v[22:23] op_sel_hi:[1,0,1]
	v_add_f32_dpp v28, v28, v28 row_ror:8 row_mask:0xf bank_mask:0xf
	v_add_f32_dpp v32, v32, v32 row_ror:8 row_mask:0xf bank_mask:0xf
	v_pk_fma_f32 v[24:25], v[176:177], v[6:7], v[24:25] op_sel_hi:[1,0,1]
	v_add_f32_dpp v28, v28, v28 quad_perm:[1,0,3,2] row_mask:0xf bank_mask:0xf
	v_add_f32_dpp v32, v32, v32 quad_perm:[1,0,3,2] row_mask:0xf bank_mask:0xf
	v_pk_fma_f32 v[26:27], v[178:179], v[6:7], v[26:27] op_sel_hi:[1,0,1]
	v_add_f32_dpp v28, v28, v28 quad_perm:[2,3,0,1] row_mask:0xf bank_mask:0xf
	v_add_f32_dpp v32, v32, v32 quad_perm:[2,3,0,1] row_mask:0xf bank_mask:0xf
	v_add_f32_e32 v39, v32, v5
	v_mov_b32_dpp v30, v28 row_half_mirror row_mask:0xf bank_mask:0xf
	v_pk_fma_f32 v[20:21], v[84:85], v[28:29], v[20:21] op_sel_hi:[1,0,1] neg_lo:[0,1,0] neg_hi:[0,1,0]
	v_pk_fma_f32 v[22:23], v[86:87], v[28:29], v[22:23] op_sel_hi:[1,0,1] neg_lo:[0,1,0] neg_hi:[0,1,0]
	v_pk_fma_f32 v[24:25], v[84:85], v[30:31], v[24:25] op_sel_hi:[1,0,1] neg_lo:[0,1,0] neg_hi:[0,1,0]
	v_pk_fma_f32 v[26:27], v[86:87], v[30:31], v[26:27] op_sel_hi:[1,0,1] neg_lo:[0,1,0] neg_hi:[0,1,0]
	ds_write_b32 v102, v39 offset:2816
	ds_read_b128 v[140:143], v195 offset:6144
	ds_read_b128 v[152:155], v195 offset:14336
	ds_read_b128 v[176:179], v195 offset:22528
	ds_read_b128 v[84:87], v195 offset:38912
	ds_read_b64 v[4:5], v196 offset:12288
	ds_read_b64 v[6:7], v36 offset:12288
	s_waitcnt lgkmcnt(7)
	v_pk_mul_f32 v[46:47], v[24:25], v[144:145] op_sel_hi:[0,1]
	v_pk_mul_f32 v[34:35], v[20:21], v[144:145] op_sel_hi:[0,1]
	v_pk_fma_f32 v[46:47], v[24:25], v[146:147], v[46:47] op_sel:[1,0,0] op_sel_hi:[1,1,1]
	v_pk_fma_f32 v[34:35], v[20:21], v[146:147], v[34:35] op_sel:[1,0,0] op_sel_hi:[1,1,1]
	v_pk_fma_f32 v[46:47], v[26:27], v[156:157], v[46:47] op_sel_hi:[0,1,1]
	v_pk_fma_f32 v[34:35], v[22:23], v[156:157], v[34:35] op_sel_hi:[0,1,1]
	v_pk_fma_f32 v[46:47], v[26:27], v[158:159], v[46:47] op_sel:[1,0,0] op_sel_hi:[1,1,1]
	v_pk_fma_f32 v[34:35], v[22:23], v[158:159], v[34:35] op_sel:[1,0,0] op_sel_hi:[1,1,1]
	v_pk_mul_f32 v[20:21], v[20:21], v[168:169]
	v_add_f32_dpp v28, v46, v34 row_half_mirror row_mask:0xf bank_mask:0xf
	v_add_f32_dpp v32, v47, v35 row_half_mirror row_mask:0xf bank_mask:0xf
	v_pk_mul_f32 v[22:23], v[22:23], v[170:171]
	v_add_f32_dpp v28, v28, v28 row_ror:8 row_mask:0xf bank_mask:0xf
	v_add_f32_dpp v32, v32, v32 row_ror:8 row_mask:0xf bank_mask:0xf
	v_pk_mul_f32 v[24:25], v[24:25], v[168:169]
	v_add_f32_dpp v28, v28, v28 quad_perm:[1,0,3,2] row_mask:0xf bank_mask:0xf
	v_add_f32_dpp v32, v32, v32 quad_perm:[1,0,3,2] row_mask:0xf bank_mask:0xf
	v_pk_mul_f32 v[26:27], v[26:27], v[170:171]
	v_add_f32_dpp v28, v28, v28 quad_perm:[2,3,0,1] row_mask:0xf bank_mask:0xf
	v_add_f32_dpp v32, v32, v32 quad_perm:[2,3,0,1] row_mask:0xf bank_mask:0xf
	v_pk_fma_f32 v[20:21], v[180:181], v[8:9], v[20:21] op_sel_hi:[1,0,1]
	v_mov_b32_dpp v30, v28 row_half_mirror row_mask:0xf bank_mask:0xf
	v_pk_fma_f32 v[22:23], v[182:183], v[8:9], v[22:23] op_sel_hi:[1,0,1]
	v_pk_fma_f32 v[24:25], v[180:181], v[10:11], v[24:25] op_sel_hi:[1,0,1]
	v_pk_fma_f32 v[26:27], v[182:183], v[10:11], v[26:27] op_sel_hi:[1,0,1]
	v_pk_fma_f32 v[20:21], v[88:89], v[28:29], v[20:21] op_sel_hi:[1,0,1] neg_lo:[0,1,0] neg_hi:[0,1,0]
	v_pk_fma_f32 v[22:23], v[90:91], v[28:29], v[22:23] op_sel_hi:[1,0,1] neg_lo:[0,1,0] neg_hi:[0,1,0]
	v_pk_fma_f32 v[24:25], v[88:89], v[30:31], v[24:25] op_sel_hi:[1,0,1] neg_lo:[0,1,0] neg_hi:[0,1,0]
	v_pk_fma_f32 v[26:27], v[90:91], v[30:31], v[26:27] op_sel_hi:[1,0,1] neg_lo:[0,1,0] neg_hi:[0,1,0]
	v_add_f32_e32 v39, v32, v9
	ds_write_b32 v102, v39 offset:2944
	ds_read_b128 v[144:147], v195 offset:6400
	ds_read_b128 v[156:159], v195 offset:14592
	ds_read_b128 v[180:183], v195 offset:22784
	ds_read_b128 v[88:91], v195 offset:39168
	ds_read_b64 v[8:9], v196 offset:12800
	ds_read_b64 v[10:11], v36 offset:12800
	s_waitcnt lgkmcnt(7)
	v_pk_mul_f32 v[46:47], v[24:25], v[140:141] op_sel_hi:[0,1]
	v_pk_mul_f32 v[34:35], v[20:21], v[140:141] op_sel_hi:[0,1]
	v_pk_fma_f32 v[46:47], v[24:25], v[142:143], v[46:47] op_sel:[1,0,0] op_sel_hi:[1,1,1]
	v_pk_fma_f32 v[34:35], v[20:21], v[142:143], v[34:35] op_sel:[1,0,0] op_sel_hi:[1,1,1]
	v_pk_fma_f32 v[46:47], v[26:27], v[152:153], v[46:47] op_sel_hi:[0,1,1]
	v_pk_fma_f32 v[34:35], v[22:23], v[152:153], v[34:35] op_sel_hi:[0,1,1]
	v_pk_fma_f32 v[46:47], v[26:27], v[154:155], v[46:47] op_sel:[1,0,0] op_sel_hi:[1,1,1]
	v_pk_fma_f32 v[34:35], v[22:23], v[154:155], v[34:35] op_sel:[1,0,0] op_sel_hi:[1,1,1]
	v_pk_fma_f32 v[20:21], v[176:177], v[4:5], v[20:21] op_sel_hi:[1,0,1]
	v_add_f32_dpp v28, v46, v34 row_half_mirror row_mask:0xf bank_mask:0xf
	v_add_f32_dpp v32, v47, v35 row_half_mirror row_mask:0xf bank_mask:0xf
	v_pk_fma_f32 v[22:23], v[178:179], v[4:5], v[22:23] op_sel_hi:[1,0,1]
	v_add_f32_dpp v28, v28, v28 row_ror:8 row_mask:0xf bank_mask:0xf
	v_add_f32_dpp v32, v32, v32 row_ror:8 row_mask:0xf bank_mask:0xf
	v_pk_fma_f32 v[24:25], v[176:177], v[6:7], v[24:25] op_sel_hi:[1,0,1]
	v_add_f32_dpp v28, v28, v28 quad_perm:[1,0,3,2] row_mask:0xf bank_mask:0xf
	v_add_f32_dpp v32, v32, v32 quad_perm:[1,0,3,2] row_mask:0xf bank_mask:0xf
	v_pk_fma_f32 v[26:27], v[178:179], v[6:7], v[26:27] op_sel_hi:[1,0,1]
	v_add_f32_dpp v28, v28, v28 quad_perm:[2,3,0,1] row_mask:0xf bank_mask:0xf
	v_add_f32_dpp v32, v32, v32 quad_perm:[2,3,0,1] row_mask:0xf bank_mask:0xf
	v_add_f32_e32 v39, v32, v5
	v_mov_b32_dpp v30, v28 row_half_mirror row_mask:0xf bank_mask:0xf
	v_pk_fma_f32 v[20:21], v[84:85], v[28:29], v[20:21] op_sel_hi:[1,0,1] neg_lo:[0,1,0] neg_hi:[0,1,0]
	v_pk_fma_f32 v[22:23], v[86:87], v[28:29], v[22:23] op_sel_hi:[1,0,1] neg_lo:[0,1,0] neg_hi:[0,1,0]
	v_pk_fma_f32 v[24:25], v[84:85], v[30:31], v[24:25] op_sel_hi:[1,0,1] neg_lo:[0,1,0] neg_hi:[0,1,0]
	v_pk_fma_f32 v[26:27], v[86:87], v[30:31], v[26:27] op_sel_hi:[1,0,1] neg_lo:[0,1,0] neg_hi:[0,1,0]
	ds_write_b32 v102, v39 offset:3072
	ds_read_b128 v[140:143], v195 offset:6656
	ds_read_b128 v[152:155], v195 offset:14848
	ds_read_b128 v[176:179], v195 offset:23040
	ds_read_b128 v[84:87], v195 offset:39424
	ds_read_b64 v[4:5], v196 offset:13312
	ds_read_b64 v[6:7], v36 offset:13312
	s_waitcnt lgkmcnt(7)
	v_pk_mul_f32 v[46:47], v[24:25], v[144:145] op_sel_hi:[0,1]
	v_pk_mul_f32 v[34:35], v[20:21], v[144:145] op_sel_hi:[0,1]
	v_pk_fma_f32 v[46:47], v[24:25], v[146:147], v[46:47] op_sel:[1,0,0] op_sel_hi:[1,1,1]
	v_pk_fma_f32 v[34:35], v[20:21], v[146:147], v[34:35] op_sel:[1,0,0] op_sel_hi:[1,1,1]
	v_pk_fma_f32 v[46:47], v[26:27], v[156:157], v[46:47] op_sel_hi:[0,1,1]
	v_pk_fma_f32 v[34:35], v[22:23], v[156:157], v[34:35] op_sel_hi:[0,1,1]
	v_pk_fma_f32 v[46:47], v[26:27], v[158:159], v[46:47] op_sel:[1,0,0] op_sel_hi:[1,1,1]
	v_pk_fma_f32 v[34:35], v[22:23], v[158:159], v[34:35] op_sel:[1,0,0] op_sel_hi:[1,1,1]
	v_pk_fma_f32 v[20:21], v[180:181], v[8:9], v[20:21] op_sel_hi:[1,0,1]
	v_add_f32_dpp v28, v46, v34 row_half_mirror row_mask:0xf bank_mask:0xf
	v_add_f32_dpp v32, v47, v35 row_half_mirror row_mask:0xf bank_mask:0xf
	v_pk_fma_f32 v[22:23], v[182:183], v[8:9], v[22:23] op_sel_hi:[1,0,1]
	v_add_f32_dpp v28, v28, v28 row_ror:8 row_mask:0xf bank_mask:0xf
	v_add_f32_dpp v32, v32, v32 row_ror:8 row_mask:0xf bank_mask:0xf
	v_pk_fma_f32 v[24:25], v[180:181], v[10:11], v[24:25] op_sel_hi:[1,0,1]
	v_add_f32_dpp v28, v28, v28 quad_perm:[1,0,3,2] row_mask:0xf bank_mask:0xf
	v_add_f32_dpp v32, v32, v32 quad_perm:[1,0,3,2] row_mask:0xf bank_mask:0xf
	v_pk_fma_f32 v[26:27], v[182:183], v[10:11], v[26:27] op_sel_hi:[1,0,1]
	v_add_f32_dpp v28, v28, v28 quad_perm:[2,3,0,1] row_mask:0xf bank_mask:0xf
	v_add_f32_dpp v32, v32, v32 quad_perm:[2,3,0,1] row_mask:0xf bank_mask:0xf
	v_add_f32_e32 v39, v32, v9
	v_mov_b32_dpp v30, v28 row_half_mirror row_mask:0xf bank_mask:0xf
	v_pk_fma_f32 v[20:21], v[88:89], v[28:29], v[20:21] op_sel_hi:[1,0,1] neg_lo:[0,1,0] neg_hi:[0,1,0]
	v_pk_fma_f32 v[22:23], v[90:91], v[28:29], v[22:23] op_sel_hi:[1,0,1] neg_lo:[0,1,0] neg_hi:[0,1,0]
	v_pk_fma_f32 v[24:25], v[88:89], v[30:31], v[24:25] op_sel_hi:[1,0,1] neg_lo:[0,1,0] neg_hi:[0,1,0]
	v_pk_fma_f32 v[26:27], v[90:91], v[30:31], v[26:27] op_sel_hi:[1,0,1] neg_lo:[0,1,0] neg_hi:[0,1,0]
	ds_write_b32 v102, v39 offset:3200
	ds_read_b128 v[144:147], v195 offset:6912
	ds_read_b128 v[156:159], v195 offset:15104
	ds_read_b128 v[168:171], v195 offset:31488
	ds_read_b128 v[180:183], v195 offset:23296
	ds_read_b128 v[88:91], v195 offset:39680
	ds_read_b64 v[8:9], v196 offset:13824
	ds_read_b64 v[10:11], v36 offset:13824
	s_waitcnt lgkmcnt(8)
	v_pk_mul_f32 v[46:47], v[24:25], v[140:141] op_sel_hi:[0,1]
	v_pk_mul_f32 v[34:35], v[20:21], v[140:141] op_sel_hi:[0,1]
	v_pk_fma_f32 v[46:47], v[24:25], v[142:143], v[46:47] op_sel:[1,0,0] op_sel_hi:[1,1,1]
	v_pk_fma_f32 v[34:35], v[20:21], v[142:143], v[34:35] op_sel:[1,0,0] op_sel_hi:[1,1,1]
	v_pk_fma_f32 v[46:47], v[26:27], v[152:153], v[46:47] op_sel_hi:[0,1,1]
	v_pk_fma_f32 v[34:35], v[22:23], v[152:153], v[34:35] op_sel_hi:[0,1,1]
	v_pk_fma_f32 v[46:47], v[26:27], v[154:155], v[46:47] op_sel:[1,0,0] op_sel_hi:[1,1,1]
	v_pk_fma_f32 v[34:35], v[22:23], v[154:155], v[34:35] op_sel:[1,0,0] op_sel_hi:[1,1,1]
	v_pk_fma_f32 v[20:21], v[176:177], v[4:5], v[20:21] op_sel_hi:[1,0,1]
	v_add_f32_dpp v28, v46, v34 row_half_mirror row_mask:0xf bank_mask:0xf
	v_add_f32_dpp v32, v47, v35 row_half_mirror row_mask:0xf bank_mask:0xf
	v_pk_fma_f32 v[22:23], v[178:179], v[4:5], v[22:23] op_sel_hi:[1,0,1]
	v_add_f32_dpp v28, v28, v28 row_ror:8 row_mask:0xf bank_mask:0xf
	v_add_f32_dpp v32, v32, v32 row_ror:8 row_mask:0xf bank_mask:0xf
	v_pk_fma_f32 v[24:25], v[176:177], v[6:7], v[24:25] op_sel_hi:[1,0,1]
	v_add_f32_dpp v28, v28, v28 quad_perm:[1,0,3,2] row_mask:0xf bank_mask:0xf
	v_add_f32_dpp v32, v32, v32 quad_perm:[1,0,3,2] row_mask:0xf bank_mask:0xf
	v_pk_fma_f32 v[26:27], v[178:179], v[6:7], v[26:27] op_sel_hi:[1,0,1]
	v_add_f32_dpp v28, v28, v28 quad_perm:[2,3,0,1] row_mask:0xf bank_mask:0xf
	v_add_f32_dpp v32, v32, v32 quad_perm:[2,3,0,1] row_mask:0xf bank_mask:0xf
	v_add_f32_e32 v39, v32, v5
	v_mov_b32_dpp v30, v28 row_half_mirror row_mask:0xf bank_mask:0xf
	v_pk_fma_f32 v[20:21], v[84:85], v[28:29], v[20:21] op_sel_hi:[1,0,1] neg_lo:[0,1,0] neg_hi:[0,1,0]
	v_pk_fma_f32 v[22:23], v[86:87], v[28:29], v[22:23] op_sel_hi:[1,0,1] neg_lo:[0,1,0] neg_hi:[0,1,0]
	v_pk_fma_f32 v[24:25], v[84:85], v[30:31], v[24:25] op_sel_hi:[1,0,1] neg_lo:[0,1,0] neg_hi:[0,1,0]
	v_pk_fma_f32 v[26:27], v[86:87], v[30:31], v[26:27] op_sel_hi:[1,0,1] neg_lo:[0,1,0] neg_hi:[0,1,0]
	ds_write_b32 v102, v39 offset:3328
	ds_read_b128 v[140:143], v195 offset:7168
	ds_read_b128 v[152:155], v195 offset:15360
	ds_read_b128 v[176:179], v195 offset:23552
	ds_read_b128 v[84:87], v195 offset:39936
	ds_read_b64 v[4:5], v196 offset:14336
	ds_read_b64 v[6:7], v36 offset:14336
	s_waitcnt lgkmcnt(7)
	v_pk_mul_f32 v[46:47], v[24:25], v[144:145] op_sel_hi:[0,1]
	v_pk_mul_f32 v[34:35], v[20:21], v[144:145] op_sel_hi:[0,1]
	v_pk_fma_f32 v[46:47], v[24:25], v[146:147], v[46:47] op_sel:[1,0,0] op_sel_hi:[1,1,1]
	v_pk_fma_f32 v[34:35], v[20:21], v[146:147], v[34:35] op_sel:[1,0,0] op_sel_hi:[1,1,1]
	v_pk_fma_f32 v[46:47], v[26:27], v[156:157], v[46:47] op_sel_hi:[0,1,1]
	v_pk_fma_f32 v[34:35], v[22:23], v[156:157], v[34:35] op_sel_hi:[0,1,1]
	v_pk_fma_f32 v[46:47], v[26:27], v[158:159], v[46:47] op_sel:[1,0,0] op_sel_hi:[1,1,1]
	v_pk_fma_f32 v[34:35], v[22:23], v[158:159], v[34:35] op_sel:[1,0,0] op_sel_hi:[1,1,1]
	v_pk_mul_f32 v[20:21], v[20:21], v[168:169]
	v_add_f32_dpp v28, v46, v34 row_half_mirror row_mask:0xf bank_mask:0xf
	v_add_f32_dpp v32, v47, v35 row_half_mirror row_mask:0xf bank_mask:0xf
	v_pk_mul_f32 v[22:23], v[22:23], v[170:171]
	v_add_f32_dpp v28, v28, v28 row_ror:8 row_mask:0xf bank_mask:0xf
	v_add_f32_dpp v32, v32, v32 row_ror:8 row_mask:0xf bank_mask:0xf
	v_pk_mul_f32 v[24:25], v[24:25], v[168:169]
	v_add_f32_dpp v28, v28, v28 quad_perm:[1,0,3,2] row_mask:0xf bank_mask:0xf
	v_add_f32_dpp v32, v32, v32 quad_perm:[1,0,3,2] row_mask:0xf bank_mask:0xf
	v_pk_mul_f32 v[26:27], v[26:27], v[170:171]
	v_add_f32_dpp v28, v28, v28 quad_perm:[2,3,0,1] row_mask:0xf bank_mask:0xf
	v_add_f32_dpp v32, v32, v32 quad_perm:[2,3,0,1] row_mask:0xf bank_mask:0xf
	v_pk_fma_f32 v[20:21], v[180:181], v[8:9], v[20:21] op_sel_hi:[1,0,1]
	v_mov_b32_dpp v30, v28 row_half_mirror row_mask:0xf bank_mask:0xf
	v_pk_fma_f32 v[22:23], v[182:183], v[8:9], v[22:23] op_sel_hi:[1,0,1]
	v_pk_fma_f32 v[24:25], v[180:181], v[10:11], v[24:25] op_sel_hi:[1,0,1]
	v_pk_fma_f32 v[26:27], v[182:183], v[10:11], v[26:27] op_sel_hi:[1,0,1]
	v_pk_fma_f32 v[20:21], v[88:89], v[28:29], v[20:21] op_sel_hi:[1,0,1] neg_lo:[0,1,0] neg_hi:[0,1,0]
	v_pk_fma_f32 v[22:23], v[90:91], v[28:29], v[22:23] op_sel_hi:[1,0,1] neg_lo:[0,1,0] neg_hi:[0,1,0]
	v_pk_fma_f32 v[24:25], v[88:89], v[30:31], v[24:25] op_sel_hi:[1,0,1] neg_lo:[0,1,0] neg_hi:[0,1,0]
	v_pk_fma_f32 v[26:27], v[90:91], v[30:31], v[26:27] op_sel_hi:[1,0,1] neg_lo:[0,1,0] neg_hi:[0,1,0]
	v_add_f32_e32 v39, v32, v9
	ds_write_b32 v102, v39 offset:3456
	ds_read_b128 v[144:147], v195 offset:7424
	ds_read_b128 v[156:159], v195 offset:15616
	ds_read_b128 v[180:183], v195 offset:23808
	ds_read_b128 v[88:91], v195 offset:40192
	ds_read_b64 v[8:9], v196 offset:14848
	ds_read_b64 v[10:11], v36 offset:14848
	s_waitcnt lgkmcnt(7)
	v_pk_mul_f32 v[46:47], v[24:25], v[140:141] op_sel_hi:[0,1]
	v_pk_mul_f32 v[34:35], v[20:21], v[140:141] op_sel_hi:[0,1]
	v_pk_fma_f32 v[46:47], v[24:25], v[142:143], v[46:47] op_sel:[1,0,0] op_sel_hi:[1,1,1]
	v_pk_fma_f32 v[34:35], v[20:21], v[142:143], v[34:35] op_sel:[1,0,0] op_sel_hi:[1,1,1]
	v_pk_fma_f32 v[46:47], v[26:27], v[152:153], v[46:47] op_sel_hi:[0,1,1]
	v_pk_fma_f32 v[34:35], v[22:23], v[152:153], v[34:35] op_sel_hi:[0,1,1]
	v_pk_fma_f32 v[46:47], v[26:27], v[154:155], v[46:47] op_sel:[1,0,0] op_sel_hi:[1,1,1]
	v_pk_fma_f32 v[34:35], v[22:23], v[154:155], v[34:35] op_sel:[1,0,0] op_sel_hi:[1,1,1]
	v_pk_fma_f32 v[20:21], v[176:177], v[4:5], v[20:21] op_sel_hi:[1,0,1]
	v_add_f32_dpp v28, v46, v34 row_half_mirror row_mask:0xf bank_mask:0xf
	v_add_f32_dpp v32, v47, v35 row_half_mirror row_mask:0xf bank_mask:0xf
	v_pk_fma_f32 v[22:23], v[178:179], v[4:5], v[22:23] op_sel_hi:[1,0,1]
	v_add_f32_dpp v28, v28, v28 row_ror:8 row_mask:0xf bank_mask:0xf
	v_add_f32_dpp v32, v32, v32 row_ror:8 row_mask:0xf bank_mask:0xf
	v_pk_fma_f32 v[24:25], v[176:177], v[6:7], v[24:25] op_sel_hi:[1,0,1]
	v_add_f32_dpp v28, v28, v28 quad_perm:[1,0,3,2] row_mask:0xf bank_mask:0xf
	v_add_f32_dpp v32, v32, v32 quad_perm:[1,0,3,2] row_mask:0xf bank_mask:0xf
	v_pk_fma_f32 v[26:27], v[178:179], v[6:7], v[26:27] op_sel_hi:[1,0,1]
	v_add_f32_dpp v28, v28, v28 quad_perm:[2,3,0,1] row_mask:0xf bank_mask:0xf
	v_add_f32_dpp v32, v32, v32 quad_perm:[2,3,0,1] row_mask:0xf bank_mask:0xf
	v_add_f32_e32 v39, v32, v5
	v_mov_b32_dpp v30, v28 row_half_mirror row_mask:0xf bank_mask:0xf
	v_pk_fma_f32 v[20:21], v[84:85], v[28:29], v[20:21] op_sel_hi:[1,0,1] neg_lo:[0,1,0] neg_hi:[0,1,0]
	v_pk_fma_f32 v[22:23], v[86:87], v[28:29], v[22:23] op_sel_hi:[1,0,1] neg_lo:[0,1,0] neg_hi:[0,1,0]
	v_pk_fma_f32 v[24:25], v[84:85], v[30:31], v[24:25] op_sel_hi:[1,0,1] neg_lo:[0,1,0] neg_hi:[0,1,0]
	v_pk_fma_f32 v[26:27], v[86:87], v[30:31], v[26:27] op_sel_hi:[1,0,1] neg_lo:[0,1,0] neg_hi:[0,1,0]
	ds_write_b32 v102, v39 offset:3584
	ds_read_b128 v[140:143], v195 offset:7680
	ds_read_b128 v[152:155], v195 offset:15872
	ds_read_b128 v[176:179], v195 offset:24064
	ds_read_b128 v[84:87], v195 offset:40448
	ds_read_b64 v[4:5], v196 offset:15360
	ds_read_b64 v[6:7], v36 offset:15360
	s_waitcnt lgkmcnt(7)
	v_pk_mul_f32 v[46:47], v[24:25], v[144:145] op_sel_hi:[0,1]
	v_pk_mul_f32 v[34:35], v[20:21], v[144:145] op_sel_hi:[0,1]
	v_pk_fma_f32 v[46:47], v[24:25], v[146:147], v[46:47] op_sel:[1,0,0] op_sel_hi:[1,1,1]
	v_pk_fma_f32 v[34:35], v[20:21], v[146:147], v[34:35] op_sel:[1,0,0] op_sel_hi:[1,1,1]
	v_pk_fma_f32 v[46:47], v[26:27], v[156:157], v[46:47] op_sel_hi:[0,1,1]
	v_pk_fma_f32 v[34:35], v[22:23], v[156:157], v[34:35] op_sel_hi:[0,1,1]
	v_pk_fma_f32 v[46:47], v[26:27], v[158:159], v[46:47] op_sel:[1,0,0] op_sel_hi:[1,1,1]
	v_pk_fma_f32 v[34:35], v[22:23], v[158:159], v[34:35] op_sel:[1,0,0] op_sel_hi:[1,1,1]
	v_pk_fma_f32 v[20:21], v[180:181], v[8:9], v[20:21] op_sel_hi:[1,0,1]
	v_add_f32_dpp v28, v46, v34 row_half_mirror row_mask:0xf bank_mask:0xf
	v_add_f32_dpp v32, v47, v35 row_half_mirror row_mask:0xf bank_mask:0xf
	v_pk_fma_f32 v[22:23], v[182:183], v[8:9], v[22:23] op_sel_hi:[1,0,1]
	v_add_f32_dpp v28, v28, v28 row_ror:8 row_mask:0xf bank_mask:0xf
	v_add_f32_dpp v32, v32, v32 row_ror:8 row_mask:0xf bank_mask:0xf
	v_pk_fma_f32 v[24:25], v[180:181], v[10:11], v[24:25] op_sel_hi:[1,0,1]
	v_add_f32_dpp v28, v28, v28 quad_perm:[1,0,3,2] row_mask:0xf bank_mask:0xf
	v_add_f32_dpp v32, v32, v32 quad_perm:[1,0,3,2] row_mask:0xf bank_mask:0xf
	v_pk_fma_f32 v[26:27], v[182:183], v[10:11], v[26:27] op_sel_hi:[1,0,1]
	v_add_f32_dpp v28, v28, v28 quad_perm:[2,3,0,1] row_mask:0xf bank_mask:0xf
	v_add_f32_dpp v32, v32, v32 quad_perm:[2,3,0,1] row_mask:0xf bank_mask:0xf
	v_add_f32_e32 v39, v32, v9
	v_mov_b32_dpp v30, v28 row_half_mirror row_mask:0xf bank_mask:0xf
	v_pk_fma_f32 v[20:21], v[88:89], v[28:29], v[20:21] op_sel_hi:[1,0,1] neg_lo:[0,1,0] neg_hi:[0,1,0]
	v_pk_fma_f32 v[22:23], v[90:91], v[28:29], v[22:23] op_sel_hi:[1,0,1] neg_lo:[0,1,0] neg_hi:[0,1,0]
	v_pk_fma_f32 v[24:25], v[88:89], v[30:31], v[24:25] op_sel_hi:[1,0,1] neg_lo:[0,1,0] neg_hi:[0,1,0]
	v_pk_fma_f32 v[26:27], v[90:91], v[30:31], v[26:27] op_sel_hi:[1,0,1] neg_lo:[0,1,0] neg_hi:[0,1,0]
	ds_write_b32 v102, v39 offset:3712
	ds_read_b128 v[144:147], v195 offset:7936
	ds_read_b128 v[156:159], v195 offset:16128
	ds_read_b128 v[168:171], v195 offset:32512
	ds_read_b128 v[180:183], v195 offset:24320
	ds_read_b128 v[88:91], v195 offset:40704
	ds_read_b64 v[8:9], v196 offset:15872
	ds_read_b64 v[10:11], v36 offset:15872
	s_waitcnt lgkmcnt(8)
	v_pk_mul_f32 v[46:47], v[24:25], v[140:141] op_sel_hi:[0,1]
	v_pk_mul_f32 v[34:35], v[20:21], v[140:141] op_sel_hi:[0,1]
	v_pk_fma_f32 v[46:47], v[24:25], v[142:143], v[46:47] op_sel:[1,0,0] op_sel_hi:[1,1,1]
	v_pk_fma_f32 v[34:35], v[20:21], v[142:143], v[34:35] op_sel:[1,0,0] op_sel_hi:[1,1,1]
	v_pk_fma_f32 v[46:47], v[26:27], v[152:153], v[46:47] op_sel_hi:[0,1,1]
	v_pk_fma_f32 v[34:35], v[22:23], v[152:153], v[34:35] op_sel_hi:[0,1,1]
	v_pk_fma_f32 v[46:47], v[26:27], v[154:155], v[46:47] op_sel:[1,0,0] op_sel_hi:[1,1,1]
	v_pk_fma_f32 v[34:35], v[22:23], v[154:155], v[34:35] op_sel:[1,0,0] op_sel_hi:[1,1,1]
	v_pk_fma_f32 v[20:21], v[176:177], v[4:5], v[20:21] op_sel_hi:[1,0,1]
	v_add_f32_dpp v28, v46, v34 row_half_mirror row_mask:0xf bank_mask:0xf
	v_add_f32_dpp v32, v47, v35 row_half_mirror row_mask:0xf bank_mask:0xf
	v_pk_fma_f32 v[22:23], v[178:179], v[4:5], v[22:23] op_sel_hi:[1,0,1]
	v_add_f32_dpp v28, v28, v28 row_ror:8 row_mask:0xf bank_mask:0xf
	v_add_f32_dpp v32, v32, v32 row_ror:8 row_mask:0xf bank_mask:0xf
	v_pk_fma_f32 v[24:25], v[176:177], v[6:7], v[24:25] op_sel_hi:[1,0,1]
	v_add_f32_dpp v28, v28, v28 quad_perm:[1,0,3,2] row_mask:0xf bank_mask:0xf
	v_add_f32_dpp v32, v32, v32 quad_perm:[1,0,3,2] row_mask:0xf bank_mask:0xf
	v_pk_fma_f32 v[26:27], v[178:179], v[6:7], v[26:27] op_sel_hi:[1,0,1]
	v_add_f32_dpp v28, v28, v28 quad_perm:[2,3,0,1] row_mask:0xf bank_mask:0xf
	v_add_f32_dpp v32, v32, v32 quad_perm:[2,3,0,1] row_mask:0xf bank_mask:0xf
	v_add_f32_e32 v39, v32, v5
	v_mov_b32_dpp v30, v28 row_half_mirror row_mask:0xf bank_mask:0xf
	v_pk_fma_f32 v[20:21], v[84:85], v[28:29], v[20:21] op_sel_hi:[1,0,1] neg_lo:[0,1,0] neg_hi:[0,1,0]
	v_pk_fma_f32 v[22:23], v[86:87], v[28:29], v[22:23] op_sel_hi:[1,0,1] neg_lo:[0,1,0] neg_hi:[0,1,0]
	v_pk_fma_f32 v[24:25], v[84:85], v[30:31], v[24:25] op_sel_hi:[1,0,1] neg_lo:[0,1,0] neg_hi:[0,1,0]
	v_pk_fma_f32 v[26:27], v[86:87], v[30:31], v[26:27] op_sel_hi:[1,0,1] neg_lo:[0,1,0] neg_hi:[0,1,0]
	ds_write_b32 v102, v39 offset:3840
	s_waitcnt lgkmcnt(1)
	v_pk_mul_f32 v[46:47], v[24:25], v[144:145] op_sel_hi:[0,1]
	v_pk_mul_f32 v[34:35], v[20:21], v[144:145] op_sel_hi:[0,1]
	v_pk_fma_f32 v[46:47], v[24:25], v[146:147], v[46:47] op_sel:[1,0,0] op_sel_hi:[1,1,1]
	v_pk_fma_f32 v[34:35], v[20:21], v[146:147], v[34:35] op_sel:[1,0,0] op_sel_hi:[1,1,1]
	v_pk_fma_f32 v[46:47], v[26:27], v[156:157], v[46:47] op_sel_hi:[0,1,1]
	v_pk_fma_f32 v[34:35], v[22:23], v[156:157], v[34:35] op_sel_hi:[0,1,1]
	v_pk_fma_f32 v[46:47], v[26:27], v[158:159], v[46:47] op_sel:[1,0,0] op_sel_hi:[1,1,1]
	v_pk_fma_f32 v[34:35], v[22:23], v[158:159], v[34:35] op_sel:[1,0,0] op_sel_hi:[1,1,1]
	v_pk_mul_f32 v[20:21], v[20:21], v[168:169]
	v_add_f32_dpp v28, v46, v34 row_half_mirror row_mask:0xf bank_mask:0xf
	v_add_f32_dpp v32, v47, v35 row_half_mirror row_mask:0xf bank_mask:0xf
	v_pk_mul_f32 v[22:23], v[22:23], v[170:171]
	v_add_f32_dpp v28, v28, v28 row_ror:8 row_mask:0xf bank_mask:0xf
	v_add_f32_dpp v32, v32, v32 row_ror:8 row_mask:0xf bank_mask:0xf
	v_pk_mul_f32 v[24:25], v[24:25], v[168:169]
	v_add_f32_dpp v28, v28, v28 quad_perm:[1,0,3,2] row_mask:0xf bank_mask:0xf
	v_add_f32_dpp v32, v32, v32 quad_perm:[1,0,3,2] row_mask:0xf bank_mask:0xf
	v_pk_mul_f32 v[26:27], v[26:27], v[170:171]
	v_add_f32_dpp v28, v28, v28 quad_perm:[2,3,0,1] row_mask:0xf bank_mask:0xf
	v_add_f32_dpp v32, v32, v32 quad_perm:[2,3,0,1] row_mask:0xf bank_mask:0xf
	v_pk_fma_f32 v[20:21], v[180:181], v[8:9], v[20:21] op_sel_hi:[1,0,1]
	v_mov_b32_dpp v30, v28 row_half_mirror row_mask:0xf bank_mask:0xf
	v_pk_fma_f32 v[22:23], v[182:183], v[8:9], v[22:23] op_sel_hi:[1,0,1]
	v_pk_fma_f32 v[24:25], v[180:181], v[10:11], v[24:25] op_sel_hi:[1,0,1]
	v_pk_fma_f32 v[26:27], v[182:183], v[10:11], v[26:27] op_sel_hi:[1,0,1]
	v_pk_fma_f32 v[20:21], v[88:89], v[28:29], v[20:21] op_sel_hi:[1,0,1] neg_lo:[0,1,0] neg_hi:[0,1,0]
	v_pk_fma_f32 v[22:23], v[90:91], v[28:29], v[22:23] op_sel_hi:[1,0,1] neg_lo:[0,1,0] neg_hi:[0,1,0]
	v_pk_fma_f32 v[24:25], v[88:89], v[30:31], v[24:25] op_sel_hi:[1,0,1] neg_lo:[0,1,0] neg_hi:[0,1,0]
	v_pk_fma_f32 v[26:27], v[90:91], v[30:31], v[26:27] op_sel_hi:[1,0,1] neg_lo:[0,1,0] neg_hi:[0,1,0]
	v_add_f32_e32 v39, v32, v9
	ds_write_b32 v102, v39 offset:3968
	s_waitcnt lgkmcnt(0)
	s_barrier
	s_add_i32 s8, s8, 1
	s_cmp_eq_u32 s8, 64
	s_cbranch_scc0 .Lrw_scan_loop
	s_setprio 0
	s_branch .LBB0_183
